# hot loop heads aligned to 256 bytes instead of 64 (same code otherwise)
# baseline (speedup 1.0000x reference)
; #define PG8_STAGE(bufoff, gbase, voff) do { _Pragma("unroll") for (int _i = 0; _i < 2; ++_i) \
;     __builtin_amdgcn_global_load_lds((const unsigned*)((const char*)(gbase) + (voff)[_i]), (LAS unsigned*)(lds + (bufoff) + ldsw + _i * 8192), 16, 0, 0); } while (0)
; #define PG8_WAIT_V(n) asm volatile("s_waitcnt vmcnt(" #n ")" ::: "memory")
; #define PG8_BAR __builtin_amdgcn_s_barrier()
; template <class Epi, class Sched>
; DI void gemm_phase(LAS unsigned char* lds, const Gemm g, const Sched& S, const Epi& E) {
;     ...
;   f32x4 acc[2][2][4][2];
; #pragma unroll
;   for (int a = 0; a < 2; ++a)
; #pragma unroll
;     for (int b = 0; b < 2; ++b)
; #pragma unroll
;       for (int m = 0; m < 4; ++m)
; #pragma unroll
;         for (int n = 0; n < 2; ++n) acc[a][b][m][n] = (f32x4){0.f, 0.f, 0.f, 0.f};
;     ...
;   PG8_STAGE(PG8_SB(0, 0), cB, voffB); PG8_STAGE(PG8_SA(0, 0), cA, voffA); PG8_STAGE(PG8_SB(0, 1), cB + hstepB, voffB); PG8_STAGE(PG8_SA(0, 1), cA + hstep, voffA);
;   if (wr == 1) PG8_BAR;
;   PG8_WAIT_V(4); PG8_BAR;
;   PG8_STAGE(PG8_SB(1, 0), cB + kstep, voffB); PG8_STAGE(PG8_SA(1, 0), cA + kstep, voffA); PG8_STAGE(PG8_SB(1, 1), cB + hstepB + kstep, voffB);
;   PG8_WAIT_V(6); PG8_BAR;
.LBB0_135:
	v_lshl_add_u64 v[4:5], s[12:13], 0, v[0:1]
	v_mov_b32_e32 v131, v1
	v_lshl_add_u64 v[6:7], s[12:13], 0, v[130:131]
	v_and_b32_e32 v132, 15, v2
	v_bfe_u32 v136, v2, 4, 2
	s_add_i32 m0, s31, 0x18000
	v_lshl_add_u64 v[2:3], v[4:5], 0, s[70:71]
	v_lshl_add_u64 v[8:9], s[14:15], 0, v[0:1]
	s_waitcnt vmcnt(4)
	s_barrier
	global_load_lds_dwordx4 v[2:3], off
	v_lshl_add_u64 v[2:3], v[6:7], 0, s[70:71]
	s_add_i32 m0, s31, 0x1a000
	s_add_i32 s37, s31, 0x8000
	v_lshl_add_u64 v[10:11], s[14:15], 0, v[130:131]
	global_load_lds_dwordx4 v[2:3], off
	v_lshl_add_u64 v[2:3], v[8:9], 0, s[70:71]
	s_mov_b32 m0, s37
	s_add_i32 s38, s31, 0xa000
	v_lshl_add_u64 v[12:13], s[18:19], 0, v[0:1]
	global_load_lds_dwordx4 v[2:3], off
	v_lshl_add_u64 v[2:3], v[10:11], 0, s[70:71]
	s_mov_b32 m0, s38
	v_lshl_add_u64 v[14:15], s[18:19], 0, v[130:131]
	global_load_lds_dwordx4 v[2:3], off
	s_add_i32 m0, s31, 0x1c000
	v_lshl_add_u64 v[2:3], v[12:13], 0, s[70:71]
	global_load_lds_dwordx4 v[2:3], off
	v_lshl_add_u64 v[2:3], v[14:15], 0, s[70:71]
	s_add_i32 m0, s31, 0x1e000
	s_lshl_b32 s18, s21, 5
	global_load_lds_dwordx4 v[2:3], off
	s_waitcnt vmcnt(6)
	s_and_b32 s27, s18, 0x60
	v_mov_b32_e32 v129, 0
	v_lshl_or_b32 v148, s20, 6, v132
	s_cmp_lt_i32 s16, 64
	v_mov_b32_e32 v128, v129
	v_mov_b32_e32 v127, v129
	v_mov_b32_e32 v126, v129
	v_mov_b32_e32 v125, v129
	v_mov_b32_e32 v124, v129
	v_mov_b32_e32 v123, v129
	v_mov_b32_e32 v122, v129
	v_mov_b32_e32 v113, v129
	v_mov_b32_e32 v112, v129
	v_mov_b32_e32 v111, v129
	v_mov_b32_e32 v110, v129
	v_mov_b32_e32 v109, v129
	v_mov_b32_e32 v108, v129
	v_mov_b32_e32 v107, v129
	v_mov_b32_e32 v106, v129
	v_mov_b32_e32 v97, v129
	v_mov_b32_e32 v96, v129
	v_mov_b32_e32 v95, v129
	v_mov_b32_e32 v94, v129
	v_mov_b32_e32 v93, v129
	v_mov_b32_e32 v92, v129
	v_mov_b32_e32 v91, v129
	v_mov_b32_e32 v90, v129
	v_mov_b32_e32 v81, v129
	v_mov_b32_e32 v80, v129
	v_mov_b32_e32 v79, v129
	v_mov_b32_e32 v78, v129
	v_mov_b32_e32 v77, v129
	v_mov_b32_e32 v76, v129
	v_mov_b32_e32 v75, v129
	v_mov_b32_e32 v74, v129
	v_mov_b32_e32 v121, v129
	v_mov_b32_e32 v120, v129
	v_mov_b32_e32 v119, v129
	v_mov_b32_e32 v118, v129
	v_mov_b32_e32 v117, v129
	v_mov_b32_e32 v116, v129
	v_mov_b32_e32 v115, v129
	v_mov_b32_e32 v114, v129
	v_mov_b32_e32 v105, v129
	v_mov_b32_e32 v104, v129
	v_mov_b32_e32 v103, v129
	v_mov_b32_e32 v102, v129
	v_mov_b32_e32 v101, v129
	v_mov_b32_e32 v100, v129
	v_mov_b32_e32 v99, v129
	v_mov_b32_e32 v98, v129
	v_mov_b32_e32 v89, v129
	v_mov_b32_e32 v88, v129
	v_mov_b32_e32 v87, v129
	v_mov_b32_e32 v86, v129
	v_mov_b32_e32 v85, v129
	v_mov_b32_e32 v84, v129
	v_mov_b32_e32 v83, v129
	v_mov_b32_e32 v82, v129
	v_mov_b32_e32 v73, v129
	v_mov_b32_e32 v72, v129
	v_mov_b32_e32 v71, v129
	v_mov_b32_e32 v70, v129
	v_mov_b32_e32 v69, v129
	v_mov_b32_e32 v68, v129
	v_mov_b32_e32 v67, v129
	v_mov_b32_e32 v66, v129
	v_mov_b32_e32 v65, v129
	v_mov_b32_e32 v64, v129
	v_mov_b32_e32 v63, v129
	v_mov_b32_e32 v62, v129
	v_mov_b32_e32 v61, v129
	v_mov_b32_e32 v60, v129
	v_mov_b32_e32 v59, v129
	v_mov_b32_e32 v58, v129
	v_mov_b32_e32 v49, v129
	v_mov_b32_e32 v48, v129
	v_mov_b32_e32 v47, v129
	v_mov_b32_e32 v46, v129
	v_mov_b32_e32 v45, v129
	v_mov_b32_e32 v44, v129
	v_mov_b32_e32 v43, v129
	v_mov_b32_e32 v42, v129
	v_mov_b32_e32 v33, v129
	v_mov_b32_e32 v32, v129
	v_mov_b32_e32 v31, v129
	v_mov_b32_e32 v30, v129
	v_mov_b32_e32 v29, v129
	v_mov_b32_e32 v28, v129
	v_mov_b32_e32 v27, v129
	v_mov_b32_e32 v26, v129
	v_mov_b32_e32 v17, v129
	v_mov_b32_e32 v16, v129
	v_mov_b32_e32 v15, v129
	v_mov_b32_e32 v14, v129
	v_mov_b32_e32 v13, v129
	v_mov_b32_e32 v12, v129
	v_mov_b32_e32 v11, v129
	v_mov_b32_e32 v10, v129
	v_mov_b32_e32 v57, v129
	v_mov_b32_e32 v56, v129
	v_mov_b32_e32 v55, v129
	v_mov_b32_e32 v54, v129
	v_mov_b32_e32 v53, v129
	v_mov_b32_e32 v52, v129
	v_mov_b32_e32 v51, v129
	v_mov_b32_e32 v50, v129
	v_mov_b32_e32 v41, v129
	v_mov_b32_e32 v40, v129
	v_mov_b32_e32 v39, v129
	v_mov_b32_e32 v38, v129
	v_mov_b32_e32 v37, v129
	v_mov_b32_e32 v36, v129
	v_mov_b32_e32 v35, v129
	v_mov_b32_e32 v34, v129
	v_mov_b32_e32 v25, v129
	v_mov_b32_e32 v24, v129
	v_mov_b32_e32 v23, v129
	v_mov_b32_e32 v22, v129
	v_mov_b32_e32 v21, v129
	v_mov_b32_e32 v20, v129
	v_mov_b32_e32 v19, v129
	v_mov_b32_e32 v18, v129
	v_mov_b32_e32 v9, v129
	v_mov_b32_e32 v8, v129
	v_mov_b32_e32 v7, v129
	v_mov_b32_e32 v6, v129
	v_mov_b32_e32 v5, v129
	v_mov_b32_e32 v4, v129
	v_mov_b32_e32 v3, v129
	v_mov_b32_e32 v2, v129
	s_barrier
;   DI bool next(int i, Unit& o) const { if (i != 0 || !valid) return false; o = u; return true; }
; template <class Epi, class Sched>
; DI void gemm_phase(LAS unsigned char* lds, const Gemm g, const Sched& S, const Epi& E) {
;     ...
;     voffA[i] = (unsigned)(R * K + C) * 2u; voffB[i] = (unsigned)(Rb * K + C) * 2u;
;   }
;   const size_t kstep = (size_t)(BK * 2);
;   const size_t hstep = (size_t)HALF * K * 2;
;   const size_t hstepB = (Epi::BMAP == 2) ? (size_t)32 * K * 2 : hstep;
;   const size_t tstep = 2 * hstep;
;   const unsigned ldsw = (unsigned)wid * 1024u;
;   const int aoff = lds_byte(wr * 64 + fr, fq * 8), boff = lds_byte(wc * 32 + fr, fq * 8);
;     ...
;   Unit cur, nxt; int ui = 0;
;   if (!S.next(0, cur)) return;
;   f32x4 acc[2][2][4][2];
; #pragma unroll
;   for (int a = 0; a < 2; ++a)
; #pragma unroll
;     for (int b = 0; b < 2; ++b)
; #pragma unroll
;       for (int m = 0; m < 4; ++m)
; #pragma unroll
;         for (int n = 0; n < 2; ++n) acc[a][b][m][n] = (f32x4){0.f, 0.f, 0.f, 0.f};
	s_cbranch_scc1 .LBB0_138
	s_lshr_b32 s18, s17, 26
	s_add_i32 s18, s16, s18
	s_ashr_i32 s39, s18, 6
	v_lshlrev_b32_e32 v2, 4, v136
	v_lshlrev_b32_e32 v3, 6, v148
	s_movk_i32 s18, 0x3c0
	v_lshlrev_b32_e32 v4, 2, v148
	v_and_or_b32 v3, v3, s18, v2
	s_lshl_b32 s18, s20, 13
	v_and_b32_e32 v4, 32, v4
	v_bitop3_b32 v3, v3, s18, v4 bitop3:0xde
	v_lshlrev_b32_e32 v4, 2, v132
	v_lshl_or_b32 v2, v132, 6, v2
	s_lshl_b32 s18, s27, 7
	v_and_b32_e32 v4, 32, v4
	v_bitop3_b32 v137, v2, s18, v4 bitop3:0xde
	s_lshl_b64 s[18:19], s[0:1], 9
	s_or_b32 s1, s18, 0x100
	s_mul_i32 s17, s1, s17
	s_mul_hi_u32 s18, s1, s16
	s_add_i32 s17, s18, s17
	s_mul_i32 s18, s19, s16
	s_add_i32 s40, s39, -2
	s_add_i32 s17, s17, s18
	s_mul_i32 s1, s1, s16
	s_add_u32 s16, s60, s1
	s_addc_u32 s17, s61, s17
	v_mov_b32_e32 v2, 0
	v_lshl_add_u64 v[132:133], s[16:17], 0, v[0:1]
	v_lshl_add_u64 v[134:135], s[16:17], 0, v[130:131]
	s_mov_b32 s1, 0
	s_mov_b64 s[16:17], 0x80
	v_add_u32_e32 v138, 16, v3
	v_mov_b32_e32 v3, v2
	v_mov_b32_e32 v4, v2
	v_mov_b32_e32 v5, v2
	v_mov_b32_e32 v6, v2
	v_mov_b32_e32 v7, v2
	v_mov_b32_e32 v8, v2
	v_mov_b32_e32 v9, v2
	v_mov_b32_e32 v18, v2
	v_mov_b32_e32 v19, v2
	v_mov_b32_e32 v20, v2
	v_mov_b32_e32 v21, v2
	v_mov_b32_e32 v22, v2
	v_mov_b32_e32 v23, v2
	v_mov_b32_e32 v24, v2
	v_mov_b32_e32 v25, v2
	v_mov_b32_e32 v34, v2
	v_mov_b32_e32 v35, v2
	v_mov_b32_e32 v36, v2
	v_mov_b32_e32 v37, v2
	v_mov_b32_e32 v38, v2
	v_mov_b32_e32 v39, v2
	v_mov_b32_e32 v40, v2
	v_mov_b32_e32 v41, v2
	v_mov_b32_e32 v50, v2
	v_mov_b32_e32 v51, v2
	v_mov_b32_e32 v52, v2
	v_mov_b32_e32 v53, v2
	v_mov_b32_e32 v54, v2
	v_mov_b32_e32 v55, v2
	v_mov_b32_e32 v56, v2
	v_mov_b32_e32 v57, v2
	v_mov_b32_e32 v10, v2
	v_mov_b32_e32 v11, v2
	v_mov_b32_e32 v12, v2
	v_mov_b32_e32 v13, v2
	v_mov_b32_e32 v14, v2
	v_mov_b32_e32 v15, v2
	v_mov_b32_e32 v16, v2
	v_mov_b32_e32 v17, v2
	v_mov_b32_e32 v26, v2
	v_mov_b32_e32 v27, v2
	v_mov_b32_e32 v28, v2
	v_mov_b32_e32 v29, v2
	v_mov_b32_e32 v30, v2
	v_mov_b32_e32 v31, v2
	v_mov_b32_e32 v32, v2
	v_mov_b32_e32 v33, v2
	v_mov_b32_e32 v42, v2
	v_mov_b32_e32 v43, v2
	v_mov_b32_e32 v44, v2
	v_mov_b32_e32 v45, v2
	v_mov_b32_e32 v46, v2
	v_mov_b32_e32 v47, v2
	v_mov_b32_e32 v48, v2
	v_mov_b32_e32 v49, v2
	v_mov_b32_e32 v58, v2
	v_mov_b32_e32 v59, v2
	v_mov_b32_e32 v60, v2
	v_mov_b32_e32 v61, v2
	v_mov_b32_e32 v62, v2
	v_mov_b32_e32 v63, v2
	v_mov_b32_e32 v64, v2
	v_mov_b32_e32 v65, v2
	v_mov_b32_e32 v66, v2
	v_mov_b32_e32 v67, v2
	v_mov_b32_e32 v68, v2
	v_mov_b32_e32 v69, v2
	v_mov_b32_e32 v70, v2
	v_mov_b32_e32 v71, v2
	v_mov_b32_e32 v72, v2
	v_mov_b32_e32 v73, v2
	v_mov_b32_e32 v82, v2
	v_mov_b32_e32 v83, v2
	v_mov_b32_e32 v84, v2
	v_mov_b32_e32 v85, v2
	v_mov_b32_e32 v86, v2
	v_mov_b32_e32 v87, v2
	v_mov_b32_e32 v88, v2
	v_mov_b32_e32 v89, v2
	v_mov_b32_e32 v98, v2
	v_mov_b32_e32 v99, v2
	v_mov_b32_e32 v100, v2
	v_mov_b32_e32 v101, v2
	v_mov_b32_e32 v102, v2
	v_mov_b32_e32 v103, v2
	v_mov_b32_e32 v104, v2
	v_mov_b32_e32 v105, v2
	v_mov_b32_e32 v114, v2
	v_mov_b32_e32 v115, v2
	v_mov_b32_e32 v116, v2
	v_mov_b32_e32 v117, v2
	v_mov_b32_e32 v118, v2
	v_mov_b32_e32 v119, v2
	v_mov_b32_e32 v120, v2
	v_mov_b32_e32 v121, v2
	v_mov_b32_e32 v74, v2
	v_mov_b32_e32 v75, v2
	v_mov_b32_e32 v76, v2
	v_mov_b32_e32 v77, v2
	v_mov_b32_e32 v78, v2
	v_mov_b32_e32 v79, v2
	v_mov_b32_e32 v80, v2
	v_mov_b32_e32 v81, v2
	v_mov_b32_e32 v90, v2
	v_mov_b32_e32 v91, v2
	v_mov_b32_e32 v92, v2
	v_mov_b32_e32 v93, v2
	v_mov_b32_e32 v94, v2
	v_mov_b32_e32 v95, v2
	v_mov_b32_e32 v96, v2
	v_mov_b32_e32 v97, v2
	v_mov_b32_e32 v106, v2
	v_mov_b32_e32 v107, v2
	v_mov_b32_e32 v108, v2
	v_mov_b32_e32 v109, v2
	v_mov_b32_e32 v110, v2
	v_mov_b32_e32 v111, v2
	v_mov_b32_e32 v112, v2
	v_mov_b32_e32 v113, v2
	v_mov_b32_e32 v122, v2
	v_mov_b32_e32 v123, v2
	v_mov_b32_e32 v124, v2
	v_mov_b32_e32 v125, v2
	v_mov_b32_e32 v126, v2
	v_mov_b32_e32 v127, v2
	v_mov_b32_e32 v128, v2
	v_mov_b32_e32 v129, v2
	.p2align	8

; #define PG8_STAGE(bufoff, gbase, voff) do { _Pragma("unroll") for (int _i = 0; _i < 2; ++_i) \
;     __builtin_amdgcn_global_load_lds((const unsigned*)((const char*)(gbase) + (voff)[_i]), (LAS unsigned*)(lds + (bufoff) + ldsw + _i * 8192), 16, 0, 0); } while (0)
; #define PG8_WAIT_V(n) asm volatile("s_waitcnt vmcnt(" #n ")" ::: "memory")
; #define PG8_BAR __builtin_amdgcn_s_barrier()
; template <class Epi, class Sched>
; DI void gemm_phase(LAS unsigned char* lds, const Gemm g, const Sched& S, const Epi& E) {
;     ...
;   f32x4 acc[2][2][4][2];
; #pragma unroll
;   for (int a = 0; a < 2; ++a)
; #pragma unroll
;     for (int b = 0; b < 2; ++b)
; #pragma unroll
;       for (int m = 0; m < 4; ++m)
; #pragma unroll
;         for (int n = 0; n < 2; ++n) acc[a][b][m][n] = (f32x4){0.f, 0.f, 0.f, 0.f};
;     ...
;   PG8_STAGE(PG8_SB(0, 0), cB, voffB); PG8_STAGE(PG8_SA(0, 0), cA, voffA); PG8_STAGE(PG8_SB(0, 1), cB + hstepB, voffB); PG8_STAGE(PG8_SA(0, 1), cA + hstep, voffA);
;   if (wr == 1) PG8_BAR;
;   PG8_WAIT_V(4); PG8_BAR;
;   PG8_STAGE(PG8_SB(1, 0), cB + kstep, voffB); PG8_STAGE(PG8_SA(1, 0), cA + kstep, voffA); PG8_STAGE(PG8_SB(1, 1), cB + hstepB + kstep, voffB);
;   PG8_WAIT_V(6); PG8_BAR;
.LBB0_151:
	v_lshl_add_u64 v[4:5], s[2:3], 0, v[0:1]
	v_mov_b32_e32 v131, v1
	v_lshl_add_u64 v[6:7], s[2:3], 0, v[130:131]
	v_and_b32_e32 v132, 15, v2
	v_bfe_u32 v136, v2, 4, 2
	s_add_i32 m0, s24, 0x18000
	v_lshl_add_u64 v[2:3], v[4:5], 0, s[70:71]
	v_lshl_add_u64 v[8:9], s[12:13], 0, v[0:1]
	s_waitcnt vmcnt(4)
	s_barrier
	global_load_lds_dwordx4 v[2:3], off
	v_lshl_add_u64 v[2:3], v[6:7], 0, s[70:71]
	s_add_i32 m0, s24, 0x1a000
	s_add_i32 s30, s24, 0x8000
	v_lshl_add_u64 v[10:11], s[12:13], 0, v[130:131]
	global_load_lds_dwordx4 v[2:3], off
	v_lshl_add_u64 v[2:3], v[8:9], 0, s[70:71]
	s_mov_b32 m0, s30
	s_add_i32 s31, s24, 0xa000
	v_lshl_add_u64 v[12:13], s[16:17], 0, v[0:1]
	global_load_lds_dwordx4 v[2:3], off
	v_lshl_add_u64 v[2:3], v[10:11], 0, s[70:71]
	s_mov_b32 m0, s31
	v_lshl_add_u64 v[14:15], s[16:17], 0, v[130:131]
	global_load_lds_dwordx4 v[2:3], off
	s_add_i32 m0, s24, 0x1c000
	v_lshl_add_u64 v[2:3], v[12:13], 0, s[70:71]
	global_load_lds_dwordx4 v[2:3], off
	v_lshl_add_u64 v[2:3], v[14:15], 0, s[70:71]
	s_add_i32 m0, s24, 0x1e000
	s_lshl_b32 s16, s19, 5
	global_load_lds_dwordx4 v[2:3], off
	s_waitcnt vmcnt(6)
	s_and_b32 s22, s16, 0x60
	v_mov_b32_e32 v129, 0
	v_lshl_or_b32 v148, s18, 6, v132
	s_cmp_lt_i32 s14, 64
	v_mov_b32_e32 v128, v129
	v_mov_b32_e32 v127, v129
	v_mov_b32_e32 v126, v129
	v_mov_b32_e32 v125, v129
	v_mov_b32_e32 v124, v129
	v_mov_b32_e32 v123, v129
	v_mov_b32_e32 v122, v129
	v_mov_b32_e32 v113, v129
	v_mov_b32_e32 v112, v129
	v_mov_b32_e32 v111, v129
	v_mov_b32_e32 v110, v129
	v_mov_b32_e32 v109, v129
	v_mov_b32_e32 v108, v129
	v_mov_b32_e32 v107, v129
	v_mov_b32_e32 v106, v129
	v_mov_b32_e32 v97, v129
	v_mov_b32_e32 v96, v129
	v_mov_b32_e32 v95, v129
	v_mov_b32_e32 v94, v129
	v_mov_b32_e32 v93, v129
	v_mov_b32_e32 v92, v129
	v_mov_b32_e32 v91, v129
	v_mov_b32_e32 v90, v129
	v_mov_b32_e32 v81, v129
	v_mov_b32_e32 v80, v129
	v_mov_b32_e32 v79, v129
	v_mov_b32_e32 v78, v129
	v_mov_b32_e32 v77, v129
	v_mov_b32_e32 v76, v129
	v_mov_b32_e32 v75, v129
	v_mov_b32_e32 v74, v129
	v_mov_b32_e32 v121, v129
	v_mov_b32_e32 v120, v129
	v_mov_b32_e32 v119, v129
	v_mov_b32_e32 v118, v129
	v_mov_b32_e32 v117, v129
	v_mov_b32_e32 v116, v129
	v_mov_b32_e32 v115, v129
	v_mov_b32_e32 v114, v129
	v_mov_b32_e32 v105, v129
	v_mov_b32_e32 v104, v129
	v_mov_b32_e32 v103, v129
	v_mov_b32_e32 v102, v129
	v_mov_b32_e32 v101, v129
	v_mov_b32_e32 v100, v129
	v_mov_b32_e32 v99, v129
	v_mov_b32_e32 v98, v129
	v_mov_b32_e32 v89, v129
	v_mov_b32_e32 v88, v129
	v_mov_b32_e32 v87, v129
	v_mov_b32_e32 v86, v129
	v_mov_b32_e32 v85, v129
	v_mov_b32_e32 v84, v129
	v_mov_b32_e32 v83, v129
	v_mov_b32_e32 v82, v129
	v_mov_b32_e32 v73, v129
	v_mov_b32_e32 v72, v129
	v_mov_b32_e32 v71, v129
	v_mov_b32_e32 v70, v129
	v_mov_b32_e32 v69, v129
	v_mov_b32_e32 v68, v129
	v_mov_b32_e32 v67, v129
	v_mov_b32_e32 v66, v129
	v_mov_b32_e32 v65, v129
	v_mov_b32_e32 v64, v129
	v_mov_b32_e32 v63, v129
	v_mov_b32_e32 v62, v129
	v_mov_b32_e32 v61, v129
	v_mov_b32_e32 v60, v129
	v_mov_b32_e32 v59, v129
	v_mov_b32_e32 v58, v129
	v_mov_b32_e32 v49, v129
	v_mov_b32_e32 v48, v129
	v_mov_b32_e32 v47, v129
	v_mov_b32_e32 v46, v129
	v_mov_b32_e32 v45, v129
	v_mov_b32_e32 v44, v129
	v_mov_b32_e32 v43, v129
	v_mov_b32_e32 v42, v129
	v_mov_b32_e32 v33, v129
	v_mov_b32_e32 v32, v129
	v_mov_b32_e32 v31, v129
	v_mov_b32_e32 v30, v129
	v_mov_b32_e32 v29, v129
	v_mov_b32_e32 v28, v129
	v_mov_b32_e32 v27, v129
	v_mov_b32_e32 v26, v129
	v_mov_b32_e32 v17, v129
	v_mov_b32_e32 v16, v129
	v_mov_b32_e32 v15, v129
	v_mov_b32_e32 v14, v129
	v_mov_b32_e32 v13, v129
	v_mov_b32_e32 v12, v129
	v_mov_b32_e32 v11, v129
	v_mov_b32_e32 v10, v129
	v_mov_b32_e32 v57, v129
	v_mov_b32_e32 v56, v129
	v_mov_b32_e32 v55, v129
	v_mov_b32_e32 v54, v129
	v_mov_b32_e32 v53, v129
	v_mov_b32_e32 v52, v129
	v_mov_b32_e32 v51, v129
	v_mov_b32_e32 v50, v129
	v_mov_b32_e32 v41, v129
	v_mov_b32_e32 v40, v129
	v_mov_b32_e32 v39, v129
	v_mov_b32_e32 v38, v129
	v_mov_b32_e32 v37, v129
	v_mov_b32_e32 v36, v129
	v_mov_b32_e32 v35, v129
	v_mov_b32_e32 v34, v129
	v_mov_b32_e32 v25, v129
	v_mov_b32_e32 v24, v129
	v_mov_b32_e32 v23, v129
	v_mov_b32_e32 v22, v129
	v_mov_b32_e32 v21, v129
	v_mov_b32_e32 v20, v129
	v_mov_b32_e32 v19, v129
	v_mov_b32_e32 v18, v129
	v_mov_b32_e32 v9, v129
	v_mov_b32_e32 v8, v129
	v_mov_b32_e32 v7, v129
	v_mov_b32_e32 v6, v129
	v_mov_b32_e32 v5, v129
	v_mov_b32_e32 v4, v129
	v_mov_b32_e32 v3, v129
	v_mov_b32_e32 v2, v129
	s_barrier
;   DI bool next(int i, Unit& o) const { if (i != 0 || !valid) return false; o = u; return true; }
; template <class Epi, class Sched>
; DI void gemm_phase(LAS unsigned char* lds, const Gemm g, const Sched& S, const Epi& E) {
;     ...
;     voffA[i] = (unsigned)(R * K + C) * 2u; voffB[i] = (unsigned)(Rb * K + C) * 2u;
;   }
;   const size_t kstep = (size_t)(BK * 2);
;   const size_t hstep = (size_t)HALF * K * 2;
;   const size_t hstepB = (Epi::BMAP == 2) ? (size_t)32 * K * 2 : hstep;
;   const size_t tstep = 2 * hstep;
;   const unsigned ldsw = (unsigned)wid * 1024u;
;   const int aoff = lds_byte(wr * 64 + fr, fq * 8), boff = lds_byte(wc * 32 + fr, fq * 8);
;     ...
;   Unit cur, nxt; int ui = 0;
;   if (!S.next(0, cur)) return;
;   f32x4 acc[2][2][4][2];
; #pragma unroll
;   for (int a = 0; a < 2; ++a)
; #pragma unroll
;     for (int b = 0; b < 2; ++b)
; #pragma unroll
;       for (int m = 0; m < 4; ++m)
; #pragma unroll
;         for (int n = 0; n < 2; ++n) acc[a][b][m][n] = (f32x4){0.f, 0.f, 0.f, 0.f};
	s_cbranch_scc1 .LBB0_154
	s_lshr_b32 s15, s15, 26
	s_add_i32 s15, s14, s15
	s_ashr_i32 s34, s15, 6
	v_lshlrev_b32_e32 v2, 4, v136
	v_lshlrev_b32_e32 v3, 6, v148
	s_movk_i32 s15, 0x3c0
	v_lshlrev_b32_e32 v4, 2, v148
	v_and_or_b32 v3, v3, s15, v2
	s_lshl_b32 s15, s18, 13
	v_and_b32_e32 v4, 32, v4
	v_bitop3_b32 v3, v3, s15, v4 bitop3:0xde
	v_lshlrev_b32_e32 v4, 2, v132
	v_lshl_or_b32 v2, v132, 6, v2
	s_lshl_b32 s15, s22, 7
	v_and_b32_e32 v4, 32, v4
	v_readlane_b32 s16, v253, 33
	s_add_i32 s35, s34, -2
	v_bitop3_b32 v137, v2, s15, v4 bitop3:0xde
	s_mul_hi_i32 s15, s16, s14
	s_mul_i32 s14, s16, s14
	s_add_u32 s14, s60, s14
	s_addc_u32 s15, s61, s15
	v_mov_b32_e32 v2, 0
	v_lshl_add_u64 v[132:133], s[14:15], 0, v[0:1]
	v_lshl_add_u64 v[134:135], s[14:15], 0, v[130:131]
	s_mov_b32 s16, 0
	s_mov_b64 s[14:15], 0x5800080
	v_add_u32_e32 v138, 16, v3
	v_mov_b32_e32 v3, v2
	v_mov_b32_e32 v4, v2
	v_mov_b32_e32 v5, v2
	v_mov_b32_e32 v6, v2
	v_mov_b32_e32 v7, v2
	v_mov_b32_e32 v8, v2
	v_mov_b32_e32 v9, v2
	v_mov_b32_e32 v18, v2
	v_mov_b32_e32 v19, v2
	v_mov_b32_e32 v20, v2
	v_mov_b32_e32 v21, v2
	v_mov_b32_e32 v22, v2
	v_mov_b32_e32 v23, v2
	v_mov_b32_e32 v24, v2
	v_mov_b32_e32 v25, v2
	v_mov_b32_e32 v34, v2
	v_mov_b32_e32 v35, v2
	v_mov_b32_e32 v36, v2
	v_mov_b32_e32 v37, v2
	v_mov_b32_e32 v38, v2
	v_mov_b32_e32 v39, v2
	v_mov_b32_e32 v40, v2
	v_mov_b32_e32 v41, v2
	v_mov_b32_e32 v50, v2
	v_mov_b32_e32 v51, v2
	v_mov_b32_e32 v52, v2
	v_mov_b32_e32 v53, v2
	v_mov_b32_e32 v54, v2
	v_mov_b32_e32 v55, v2
	v_mov_b32_e32 v56, v2
	v_mov_b32_e32 v57, v2
	v_mov_b32_e32 v10, v2
	v_mov_b32_e32 v11, v2
	v_mov_b32_e32 v12, v2
	v_mov_b32_e32 v13, v2
	v_mov_b32_e32 v14, v2
	v_mov_b32_e32 v15, v2
	v_mov_b32_e32 v16, v2
	v_mov_b32_e32 v17, v2
	v_mov_b32_e32 v26, v2
	v_mov_b32_e32 v27, v2
	v_mov_b32_e32 v28, v2
	v_mov_b32_e32 v29, v2
	v_mov_b32_e32 v30, v2
	v_mov_b32_e32 v31, v2
	v_mov_b32_e32 v32, v2
	v_mov_b32_e32 v33, v2
	v_mov_b32_e32 v42, v2
	v_mov_b32_e32 v43, v2
	v_mov_b32_e32 v44, v2
	v_mov_b32_e32 v45, v2
	v_mov_b32_e32 v46, v2
	v_mov_b32_e32 v47, v2
	v_mov_b32_e32 v48, v2
	v_mov_b32_e32 v49, v2
	v_mov_b32_e32 v58, v2
	v_mov_b32_e32 v59, v2
	v_mov_b32_e32 v60, v2
	v_mov_b32_e32 v61, v2
	v_mov_b32_e32 v62, v2
	v_mov_b32_e32 v63, v2
	v_mov_b32_e32 v64, v2
	v_mov_b32_e32 v65, v2
	v_mov_b32_e32 v66, v2
	v_mov_b32_e32 v67, v2
	v_mov_b32_e32 v68, v2
	v_mov_b32_e32 v69, v2
	v_mov_b32_e32 v70, v2
	v_mov_b32_e32 v71, v2
	v_mov_b32_e32 v72, v2
	v_mov_b32_e32 v73, v2
	v_mov_b32_e32 v82, v2
	v_mov_b32_e32 v83, v2
	v_mov_b32_e32 v84, v2
	v_mov_b32_e32 v85, v2
	v_mov_b32_e32 v86, v2
	v_mov_b32_e32 v87, v2
	v_mov_b32_e32 v88, v2
	v_mov_b32_e32 v89, v2
	v_mov_b32_e32 v98, v2
	v_mov_b32_e32 v99, v2
	v_mov_b32_e32 v100, v2
	v_mov_b32_e32 v101, v2
	v_mov_b32_e32 v102, v2
	v_mov_b32_e32 v103, v2
	v_mov_b32_e32 v104, v2
	v_mov_b32_e32 v105, v2
	v_mov_b32_e32 v114, v2
	v_mov_b32_e32 v115, v2
	v_mov_b32_e32 v116, v2
	v_mov_b32_e32 v117, v2
	v_mov_b32_e32 v118, v2
	v_mov_b32_e32 v119, v2
	v_mov_b32_e32 v120, v2
	v_mov_b32_e32 v121, v2
	v_mov_b32_e32 v74, v2
	v_mov_b32_e32 v75, v2
	v_mov_b32_e32 v76, v2
	v_mov_b32_e32 v77, v2
	v_mov_b32_e32 v78, v2
	v_mov_b32_e32 v79, v2
	v_mov_b32_e32 v80, v2
	v_mov_b32_e32 v81, v2
	v_mov_b32_e32 v90, v2
	v_mov_b32_e32 v91, v2
	v_mov_b32_e32 v92, v2
	v_mov_b32_e32 v93, v2
	v_mov_b32_e32 v94, v2
	v_mov_b32_e32 v95, v2
	v_mov_b32_e32 v96, v2
	v_mov_b32_e32 v97, v2
	v_mov_b32_e32 v106, v2
	v_mov_b32_e32 v107, v2
	v_mov_b32_e32 v108, v2
	v_mov_b32_e32 v109, v2
	v_mov_b32_e32 v110, v2
	v_mov_b32_e32 v111, v2
	v_mov_b32_e32 v112, v2
	v_mov_b32_e32 v113, v2
	v_mov_b32_e32 v122, v2
	v_mov_b32_e32 v123, v2
	v_mov_b32_e32 v124, v2
	v_mov_b32_e32 v125, v2
	v_mov_b32_e32 v126, v2
	v_mov_b32_e32 v127, v2
	v_mov_b32_e32 v128, v2
	v_mov_b32_e32 v129, v2
	.p2align	8

; template <class Epi, class Sched>
; DI void gemm_phase(LAS unsigned char* lds, const Gemm g, const Sched& S, const Epi& E) {
;     ...
;     if (!has_next) break;
; #pragma unroll
;     for (int a = 0; a < 2; ++a)
; #pragma unroll
;       for (int b = 0; b < 2; ++b)
; #pragma unroll
;         for (int m = 0; m < 4; ++m)
; #pragma unroll
;           for (int n = 0; n < 2; ++n) acc[a][b][m][n] = (f32x4){0.f, 0.f, 0.f, 0.f};
;     cur = nxt; cA = nA; cB = nB; ++ui;
.LBB0_176:
	s_waitcnt vmcnt(8)
	v_mov_b32_e32 v125, 0
	s_andn2_b64 vcc, exec, s[16:17]
	v_mov_b32_e32 v124, v125
	v_mov_b32_e32 v123, v125
	v_mov_b32_e32 v122, v125
	v_mov_b32_e32 v121, v125
	v_mov_b32_e32 v120, v125
	v_mov_b32_e32 v119, v125
	v_mov_b32_e32 v118, v125
	v_mov_b32_e32 v113, v125
	v_mov_b32_e32 v112, v125
	v_mov_b32_e32 v111, v125
	v_mov_b32_e32 v110, v125
	v_mov_b32_e32 v105, v125
	v_mov_b32_e32 v104, v125
	v_mov_b32_e32 v103, v125
	v_mov_b32_e32 v102, v125
	v_mov_b32_e32 v97, v125
	v_mov_b32_e32 v96, v125
	v_mov_b32_e32 v95, v125
	v_mov_b32_e32 v94, v125
	v_mov_b32_e32 v89, v125
	v_mov_b32_e32 v88, v125
	v_mov_b32_e32 v87, v125
	v_mov_b32_e32 v86, v125
	v_mov_b32_e32 v81, v125
	v_mov_b32_e32 v80, v125
	v_mov_b32_e32 v79, v125
	v_mov_b32_e32 v78, v125
	v_mov_b32_e32 v73, v125
	v_mov_b32_e32 v72, v125
	v_mov_b32_e32 v71, v125
	v_mov_b32_e32 v70, v125
	v_mov_b32_e32 v129, v125
	v_mov_b32_e32 v128, v125
	v_mov_b32_e32 v127, v125
	v_mov_b32_e32 v126, v125
	v_mov_b32_e32 v117, v125
	v_mov_b32_e32 v116, v125
	v_mov_b32_e32 v115, v125
	v_mov_b32_e32 v114, v125
	v_mov_b32_e32 v109, v125
	v_mov_b32_e32 v108, v125
	v_mov_b32_e32 v107, v125
	v_mov_b32_e32 v106, v125
	v_mov_b32_e32 v101, v125
	v_mov_b32_e32 v100, v125
	v_mov_b32_e32 v99, v125
	v_mov_b32_e32 v98, v125
	v_mov_b32_e32 v93, v125
	v_mov_b32_e32 v92, v125
	v_mov_b32_e32 v91, v125
	v_mov_b32_e32 v90, v125
	v_mov_b32_e32 v85, v125
	v_mov_b32_e32 v84, v125
	v_mov_b32_e32 v83, v125
	v_mov_b32_e32 v82, v125
	v_mov_b32_e32 v77, v125
	v_mov_b32_e32 v76, v125
	v_mov_b32_e32 v75, v125
	v_mov_b32_e32 v74, v125
	v_mov_b32_e32 v69, v125
	v_mov_b32_e32 v68, v125
	v_mov_b32_e32 v67, v125
	v_mov_b32_e32 v66, v125
	v_mov_b32_e32 v65, v125
	v_mov_b32_e32 v64, v125
	v_mov_b32_e32 v63, v125
	v_mov_b32_e32 v62, v125
	v_mov_b32_e32 v57, v125
	v_mov_b32_e32 v56, v125
	v_mov_b32_e32 v55, v125
	v_mov_b32_e32 v54, v125
	v_mov_b32_e32 v49, v125
	v_mov_b32_e32 v48, v125
	v_mov_b32_e32 v47, v125
	v_mov_b32_e32 v46, v125
	v_mov_b32_e32 v41, v125
	v_mov_b32_e32 v40, v125
	v_mov_b32_e32 v39, v125
	v_mov_b32_e32 v38, v125
	v_mov_b32_e32 v33, v125
	v_mov_b32_e32 v32, v125
	v_mov_b32_e32 v31, v125
	v_mov_b32_e32 v30, v125
	v_mov_b32_e32 v25, v125
	v_mov_b32_e32 v24, v125
	v_mov_b32_e32 v23, v125
	v_mov_b32_e32 v22, v125
	v_mov_b32_e32 v17, v125
	v_mov_b32_e32 v16, v125
	v_mov_b32_e32 v15, v125
	v_mov_b32_e32 v14, v125
	v_mov_b32_e32 v9, v125
	v_mov_b32_e32 v8, v125
	v_mov_b32_e32 v7, v125
	v_mov_b32_e32 v6, v125
	v_mov_b32_e32 v61, v125
	v_mov_b32_e32 v60, v125
	v_mov_b32_e32 v59, v125
	v_mov_b32_e32 v58, v125
	v_mov_b32_e32 v53, v125
	v_mov_b32_e32 v52, v125
	v_mov_b32_e32 v51, v125
	v_mov_b32_e32 v50, v125
	v_mov_b32_e32 v45, v125
	v_mov_b32_e32 v44, v125
	v_mov_b32_e32 v43, v125
	v_mov_b32_e32 v42, v125
	v_mov_b32_e32 v37, v125
	v_mov_b32_e32 v36, v125
	v_mov_b32_e32 v35, v125
	v_mov_b32_e32 v34, v125
	v_mov_b32_e32 v29, v125
	v_mov_b32_e32 v28, v125
	v_mov_b32_e32 v27, v125
	v_mov_b32_e32 v26, v125
	v_mov_b32_e32 v21, v125
	v_mov_b32_e32 v20, v125
	v_mov_b32_e32 v19, v125
	v_mov_b32_e32 v18, v125
	v_mov_b32_e32 v13, v125
	v_mov_b32_e32 v12, v125
	v_mov_b32_e32 v11, v125
	v_mov_b32_e32 v10, v125
	v_mov_b32_e32 v5, v125
	v_mov_b32_e32 v4, v125
	v_mov_b32_e32 v3, v125
	v_mov_b32_e32 v2, v125
	s_cbranch_vccnz .LBB0_162
	s_add_u32 s22, s22, 0x80
	s_addc_u32 s23, s23, 0
	s_add_u32 s49, s24, 0x100
	v_mov_b32_e32 v2, 0
	s_addc_u32 s50, s25, 0
	s_mov_b32 s24, 0
	v_mov_b32_e32 v3, v2
	v_mov_b32_e32 v4, v2
	v_mov_b32_e32 v5, v2
	v_mov_b32_e32 v10, v2
	v_mov_b32_e32 v11, v2
	v_mov_b32_e32 v12, v2
	v_mov_b32_e32 v13, v2
	v_mov_b32_e32 v18, v2
	v_mov_b32_e32 v19, v2
	v_mov_b32_e32 v20, v2
	v_mov_b32_e32 v21, v2
	v_mov_b32_e32 v26, v2
	v_mov_b32_e32 v27, v2
	v_mov_b32_e32 v28, v2
	v_mov_b32_e32 v29, v2
	v_mov_b32_e32 v34, v2
	v_mov_b32_e32 v35, v2
	v_mov_b32_e32 v36, v2
	v_mov_b32_e32 v37, v2
	v_mov_b32_e32 v42, v2
	v_mov_b32_e32 v43, v2
	v_mov_b32_e32 v44, v2
	v_mov_b32_e32 v45, v2
	v_mov_b32_e32 v50, v2
	v_mov_b32_e32 v51, v2
	v_mov_b32_e32 v52, v2
	v_mov_b32_e32 v53, v2
	v_mov_b32_e32 v58, v2
	v_mov_b32_e32 v59, v2
	v_mov_b32_e32 v60, v2
	v_mov_b32_e32 v61, v2
	v_mov_b32_e32 v6, v2
	v_mov_b32_e32 v7, v2
	v_mov_b32_e32 v8, v2
	v_mov_b32_e32 v9, v2
	v_mov_b32_e32 v14, v2
	v_mov_b32_e32 v15, v2
	v_mov_b32_e32 v16, v2
	v_mov_b32_e32 v17, v2
	v_mov_b32_e32 v22, v2
	v_mov_b32_e32 v23, v2
	v_mov_b32_e32 v24, v2
	v_mov_b32_e32 v25, v2
	v_mov_b32_e32 v30, v2
	v_mov_b32_e32 v31, v2
	v_mov_b32_e32 v32, v2
	v_mov_b32_e32 v33, v2
	v_mov_b32_e32 v38, v2
	v_mov_b32_e32 v39, v2
	v_mov_b32_e32 v40, v2
	v_mov_b32_e32 v41, v2
	v_mov_b32_e32 v46, v2
	v_mov_b32_e32 v47, v2
	v_mov_b32_e32 v48, v2
	v_mov_b32_e32 v49, v2
	v_mov_b32_e32 v54, v2
	v_mov_b32_e32 v55, v2
	v_mov_b32_e32 v56, v2
	v_mov_b32_e32 v57, v2
	v_mov_b32_e32 v62, v2
	v_mov_b32_e32 v63, v2
	v_mov_b32_e32 v64, v2
	v_mov_b32_e32 v65, v2
	v_mov_b32_e32 v66, v2
	v_mov_b32_e32 v67, v2
	v_mov_b32_e32 v68, v2
	v_mov_b32_e32 v69, v2
	v_mov_b32_e32 v74, v2
	v_mov_b32_e32 v75, v2
	v_mov_b32_e32 v76, v2
	v_mov_b32_e32 v77, v2
	v_mov_b32_e32 v82, v2
	v_mov_b32_e32 v83, v2
	v_mov_b32_e32 v84, v2
	v_mov_b32_e32 v85, v2
	v_mov_b32_e32 v90, v2
	v_mov_b32_e32 v91, v2
	v_mov_b32_e32 v92, v2
	v_mov_b32_e32 v93, v2
	v_mov_b32_e32 v98, v2
	v_mov_b32_e32 v99, v2
	v_mov_b32_e32 v100, v2
	v_mov_b32_e32 v101, v2
	v_mov_b32_e32 v106, v2
	v_mov_b32_e32 v107, v2
	v_mov_b32_e32 v108, v2
	v_mov_b32_e32 v109, v2
	v_mov_b32_e32 v114, v2
	v_mov_b32_e32 v115, v2
	v_mov_b32_e32 v116, v2
	v_mov_b32_e32 v117, v2
	v_mov_b32_e32 v126, v2
	v_mov_b32_e32 v127, v2
	v_mov_b32_e32 v128, v2
	v_mov_b32_e32 v129, v2
	v_mov_b32_e32 v70, v2
	v_mov_b32_e32 v71, v2
	v_mov_b32_e32 v72, v2
	v_mov_b32_e32 v73, v2
	v_mov_b32_e32 v78, v2
	v_mov_b32_e32 v79, v2
	v_mov_b32_e32 v80, v2
	v_mov_b32_e32 v81, v2
	v_mov_b32_e32 v86, v2
	v_mov_b32_e32 v87, v2
	v_mov_b32_e32 v88, v2
	v_mov_b32_e32 v89, v2
	v_mov_b32_e32 v94, v2
	v_mov_b32_e32 v95, v2
	v_mov_b32_e32 v96, v2
	v_mov_b32_e32 v97, v2
	v_mov_b32_e32 v102, v2
	v_mov_b32_e32 v103, v2
	v_mov_b32_e32 v104, v2
	v_mov_b32_e32 v105, v2
	v_mov_b32_e32 v110, v2
	v_mov_b32_e32 v111, v2
	v_mov_b32_e32 v112, v2
	v_mov_b32_e32 v113, v2
	v_mov_b32_e32 v118, v2
	v_mov_b32_e32 v119, v2
	v_mov_b32_e32 v120, v2
	v_mov_b32_e32 v121, v2
	v_mov_b32_e32 v122, v2
	v_mov_b32_e32 v123, v2
	v_mov_b32_e32 v124, v2
	v_mov_b32_e32 v125, v2
	.p2align	8

; #define PG8_STAGE(bufoff, gbase, voff) do { _Pragma("unroll") for (int _i = 0; _i < 2; ++_i) \
;     __builtin_amdgcn_global_load_lds((const unsigned*)((const char*)(gbase) + (voff)[_i]), (LAS unsigned*)(lds + (bufoff) + ldsw + _i * 8192), 16, 0, 0); } while (0)
; #define PG8_WAIT_V(n) asm volatile("s_waitcnt vmcnt(" #n ")" ::: "memory")
; #define PG8_BAR __builtin_amdgcn_s_barrier()
; template <class Epi, class Sched>
; DI void gemm_phase(LAS unsigned char* lds, const Gemm g, const Sched& S, const Epi& E) {
;     ...
;   f32x4 acc[2][2][4][2];
; #pragma unroll
;   for (int a = 0; a < 2; ++a)
; #pragma unroll
;     for (int b = 0; b < 2; ++b)
; #pragma unroll
;       for (int m = 0; m < 4; ++m)
; #pragma unroll
;         for (int n = 0; n < 2; ++n) acc[a][b][m][n] = (f32x4){0.f, 0.f, 0.f, 0.f};
;   bf16x8 At[4][2], B0[2][2], B1[2][2];
;   const char* cA = (const char*)g.A + (size_t)cur.pm * tstep; const char* cB = (const char*)g.Bt + (size_t)cur.pn * tstep;
;   PG8_STAGE(PG8_SB(0, 0), cB, voffB); PG8_STAGE(PG8_SA(0, 0), cA, voffA); PG8_STAGE(PG8_SB(0, 1), cB + hstepB, voffB); PG8_STAGE(PG8_SA(0, 1), cA + hstep, voffA);
;   if (wr == 1) PG8_BAR;
;   PG8_WAIT_V(4); PG8_BAR;
;   PG8_STAGE(PG8_SB(1, 0), cB + kstep, voffB); PG8_STAGE(PG8_SA(1, 0), cA + kstep, voffA); PG8_STAGE(PG8_SB(1, 1), cB + hstepB + kstep, voffB);
;   PG8_WAIT_V(6); PG8_BAR;
.LBB0_189:
	v_lshl_add_u64 v[4:5], s[2:3], 0, v[0:1]
	v_mov_b32_e32 v131, v1
	v_and_b32_e32 v142, 15, v2
	v_lshrrev_b32_e32 v2, 1, v2
	v_lshl_add_u64 v[6:7], s[2:3], 0, v[130:131]
	v_mov_b32_e32 v135, v1
	v_and_b32_e32 v140, 24, v2
	s_add_i32 m0, s23, 0x18000
	v_lshl_add_u64 v[2:3], v[4:5], 0, s[70:71]
	v_lshl_add_u64 v[8:9], s[12:13], 0, v[134:135]
	v_mov_b32_e32 v133, v1
	s_waitcnt vmcnt(4)
	s_barrier
	global_load_lds_dwordx4 v[2:3], off
	v_lshl_add_u64 v[2:3], v[6:7], 0, s[70:71]
	s_add_i32 m0, s23, 0x1a000
	s_add_i32 s27, s23, 0x8000
	v_lshl_add_u64 v[10:11], s[12:13], 0, v[132:133]
	global_load_lds_dwordx4 v[2:3], off
	v_lshl_add_u64 v[2:3], v[8:9], 0, s[70:71]
	s_mov_b32 m0, s27
	s_add_i32 s29, s23, 0xa000
	v_lshl_add_u64 v[12:13], s[16:17], 0, v[0:1]
	global_load_lds_dwordx4 v[2:3], off
	v_lshl_add_u64 v[2:3], v[10:11], 0, s[70:71]
	s_mov_b32 m0, s29
	v_lshl_add_u64 v[14:15], s[16:17], 0, v[130:131]
	global_load_lds_dwordx4 v[2:3], off
	s_add_i32 m0, s23, 0x1c000
	v_lshl_add_u64 v[2:3], v[12:13], 0, s[70:71]
	global_load_lds_dwordx4 v[2:3], off
	v_lshl_add_u64 v[2:3], v[14:15], 0, s[70:71]
	s_add_i32 m0, s23, 0x1e000
	s_lshl_b32 s16, s19, 5
	global_load_lds_dwordx4 v[2:3], off
	s_waitcnt vmcnt(6)
	s_and_b32 s21, s16, 0x60
	v_mov_b32_e32 v129, 0
	v_lshl_or_b32 v141, s18, 6, v142
	s_cmp_lt_i32 s14, 64
	v_mov_b32_e32 v128, v129
	v_mov_b32_e32 v127, v129
	v_mov_b32_e32 v126, v129
	v_mov_b32_e32 v121, v129
	v_mov_b32_e32 v120, v129
	v_mov_b32_e32 v119, v129
	v_mov_b32_e32 v118, v129
	v_mov_b32_e32 v113, v129
	v_mov_b32_e32 v112, v129
	v_mov_b32_e32 v111, v129
	v_mov_b32_e32 v110, v129
	v_mov_b32_e32 v105, v129
	v_mov_b32_e32 v104, v129
	v_mov_b32_e32 v103, v129
	v_mov_b32_e32 v102, v129
	v_mov_b32_e32 v97, v129
	v_mov_b32_e32 v96, v129
	v_mov_b32_e32 v95, v129
	v_mov_b32_e32 v94, v129
	v_mov_b32_e32 v89, v129
	v_mov_b32_e32 v88, v129
	v_mov_b32_e32 v87, v129
	v_mov_b32_e32 v86, v129
	v_mov_b32_e32 v81, v129
	v_mov_b32_e32 v80, v129
	v_mov_b32_e32 v79, v129
	v_mov_b32_e32 v78, v129
	v_mov_b32_e32 v73, v129
	v_mov_b32_e32 v72, v129
	v_mov_b32_e32 v71, v129
	v_mov_b32_e32 v70, v129
	v_mov_b32_e32 v125, v129
	v_mov_b32_e32 v124, v129
	v_mov_b32_e32 v123, v129
	v_mov_b32_e32 v122, v129
	v_mov_b32_e32 v117, v129
	v_mov_b32_e32 v116, v129
	v_mov_b32_e32 v115, v129
	v_mov_b32_e32 v114, v129
	v_mov_b32_e32 v109, v129
	v_mov_b32_e32 v108, v129
	v_mov_b32_e32 v107, v129
	v_mov_b32_e32 v106, v129
	v_mov_b32_e32 v101, v129
	v_mov_b32_e32 v100, v129
	v_mov_b32_e32 v99, v129
	v_mov_b32_e32 v98, v129
	v_mov_b32_e32 v93, v129
	v_mov_b32_e32 v92, v129
	v_mov_b32_e32 v91, v129
	v_mov_b32_e32 v90, v129
	v_mov_b32_e32 v85, v129
	v_mov_b32_e32 v84, v129
	v_mov_b32_e32 v83, v129
	v_mov_b32_e32 v82, v129
	v_mov_b32_e32 v77, v129
	v_mov_b32_e32 v76, v129
	v_mov_b32_e32 v75, v129
	v_mov_b32_e32 v74, v129
	v_mov_b32_e32 v69, v129
	v_mov_b32_e32 v68, v129
	v_mov_b32_e32 v67, v129
	v_mov_b32_e32 v66, v129
	v_mov_b32_e32 v65, v129
	v_mov_b32_e32 v64, v129
	v_mov_b32_e32 v63, v129
	v_mov_b32_e32 v62, v129
	v_mov_b32_e32 v57, v129
	v_mov_b32_e32 v56, v129
	v_mov_b32_e32 v55, v129
	v_mov_b32_e32 v54, v129
	v_mov_b32_e32 v49, v129
	v_mov_b32_e32 v48, v129
	v_mov_b32_e32 v47, v129
	v_mov_b32_e32 v46, v129
	v_mov_b32_e32 v41, v129
	v_mov_b32_e32 v40, v129
	v_mov_b32_e32 v39, v129
	v_mov_b32_e32 v38, v129
	v_mov_b32_e32 v33, v129
	v_mov_b32_e32 v32, v129
	v_mov_b32_e32 v31, v129
	v_mov_b32_e32 v30, v129
	v_mov_b32_e32 v25, v129
	v_mov_b32_e32 v24, v129
	v_mov_b32_e32 v23, v129
	v_mov_b32_e32 v22, v129
	v_mov_b32_e32 v17, v129
	v_mov_b32_e32 v16, v129
	v_mov_b32_e32 v15, v129
	v_mov_b32_e32 v14, v129
	v_mov_b32_e32 v9, v129
	v_mov_b32_e32 v8, v129
	v_mov_b32_e32 v7, v129
	v_mov_b32_e32 v6, v129
	v_mov_b32_e32 v61, v129
	v_mov_b32_e32 v60, v129
	v_mov_b32_e32 v59, v129
	v_mov_b32_e32 v58, v129
	v_mov_b32_e32 v53, v129
	v_mov_b32_e32 v52, v129
	v_mov_b32_e32 v51, v129
	v_mov_b32_e32 v50, v129
	v_mov_b32_e32 v45, v129
	v_mov_b32_e32 v44, v129
	v_mov_b32_e32 v43, v129
	v_mov_b32_e32 v42, v129
	v_mov_b32_e32 v37, v129
	v_mov_b32_e32 v36, v129
	v_mov_b32_e32 v35, v129
	v_mov_b32_e32 v34, v129
	v_mov_b32_e32 v29, v129
	v_mov_b32_e32 v28, v129
	v_mov_b32_e32 v27, v129
	v_mov_b32_e32 v26, v129
	v_mov_b32_e32 v21, v129
	v_mov_b32_e32 v20, v129
	v_mov_b32_e32 v19, v129
	v_mov_b32_e32 v18, v129
	v_mov_b32_e32 v13, v129
	v_mov_b32_e32 v12, v129
	v_mov_b32_e32 v11, v129
	v_mov_b32_e32 v10, v129
	v_mov_b32_e32 v5, v129
	v_mov_b32_e32 v4, v129
	v_mov_b32_e32 v3, v129
	v_mov_b32_e32 v2, v129
	s_barrier
; template <class Epi, class Sched>
; DI void gemm_phase(LAS unsigned char* lds, const Gemm g, const Sched& S, const Epi& E) {
;     ...
;   const int nt = K / BK;
;   unsigned voffA[2], voffB[2];
; #pragma unroll
;   for (int i = 0; i < 2; ++i) {
;     int R, C; stage_rc(tid * 16 + i * 8192, R, C);
;     int Rb = R;
;     if (Epi::BMAP == 1) Rb = (R & ~31) + perm32(R & 31);
;     if (Epi::BMAP == 2) Rb = 64 * (R >> 5) + perm32(R & 31);
;     voffA[i] = (unsigned)(R * K + C) * 2u; voffB[i] = (unsigned)(Rb * K + C) * 2u;
;   }
;   const size_t kstep = (size_t)(BK * 2);
;   const size_t hstep = (size_t)HALF * K * 2;
;   const size_t hstepB = (Epi::BMAP == 2) ? (size_t)32 * K * 2 : hstep;
;   const size_t tstep = 2 * hstep;
;   const unsigned ldsw = (unsigned)wid * 1024u;
;   const int aoff = lds_byte(wr * 64 + fr, fq * 8), boff = lds_byte(wc * 32 + fr, fq * 8);
;     ...
; #pragma unroll
;   for (int a = 0; a < 2; ++a)
; #pragma unroll
;     for (int b = 0; b < 2; ++b)
; #pragma unroll
;       for (int m = 0; m < 4; ++m)
; #pragma unroll
;         for (int n = 0; n < 2; ++n) acc[a][b][m][n] = (f32x4){0.f, 0.f, 0.f, 0.f};
	s_cbranch_scc1 .LBB0_192
	s_lshr_b32 s15, s15, 26
	s_add_i32 s15, s14, s15
	s_ashr_i32 s30, s15, 6
	v_lshlrev_b32_e32 v2, 6, v141
	v_lshlrev_b32_e32 v3, 1, v140
	s_movk_i32 s15, 0x3c0
	v_lshlrev_b32_e32 v4, 2, v141
	v_and_or_b32 v2, v2, s15, v3
	s_lshl_b32 s15, s18, 13
	v_and_b32_e32 v4, 32, v4
	v_bitop3_b32 v4, v2, s15, v4 bitop3:0xde
	v_lshl_or_b32 v2, v142, 6, v3
	v_lshlrev_b32_e32 v3, 2, v142
	s_lshl_b32 s15, s21, 7
	v_and_b32_e32 v3, 32, v3
	v_readlane_b32 s16, v253, 35
	s_add_i32 s31, s30, -2
	v_bitop3_b32 v142, v2, s15, v3 bitop3:0xde
	s_mul_hi_i32 s15, s16, s14
	s_mul_i32 s14, s16, s14
	v_add_u32_e32 v2, v144, v136
	s_add_u32 s14, s86, s14
	v_add_lshl_u32 v2, v2, v137, 1
	v_mov_b32_e32 v3, v1
	s_addc_u32 s15, s87, s15
	v_lshl_add_u64 v[136:137], s[14:15], 0, v[2:3]
	v_add_u32_e32 v2, v143, v138
	v_add_lshl_u32 v2, v2, v139, 1
	v_lshl_add_u64 v[138:139], s[14:15], 0, v[2:3]
	v_mov_b32_e32 v2, 0
	s_mov_b32 s16, 0
	s_mov_b64 s[14:15], 0x2000080
	v_add_u32_e32 v143, 16, v4
	v_mov_b32_e32 v3, v2
	v_mov_b32_e32 v4, v2
	v_mov_b32_e32 v5, v2
	v_mov_b32_e32 v10, v2
	v_mov_b32_e32 v11, v2
	v_mov_b32_e32 v12, v2
	v_mov_b32_e32 v13, v2
	v_mov_b32_e32 v18, v2
	v_mov_b32_e32 v19, v2
	v_mov_b32_e32 v20, v2
	v_mov_b32_e32 v21, v2
	v_mov_b32_e32 v26, v2
	v_mov_b32_e32 v27, v2
	v_mov_b32_e32 v28, v2
	v_mov_b32_e32 v29, v2
	v_mov_b32_e32 v34, v2
	v_mov_b32_e32 v35, v2
	v_mov_b32_e32 v36, v2
	v_mov_b32_e32 v37, v2
	v_mov_b32_e32 v42, v2
	v_mov_b32_e32 v43, v2
	v_mov_b32_e32 v44, v2
	v_mov_b32_e32 v45, v2
	v_mov_b32_e32 v50, v2
	v_mov_b32_e32 v51, v2
	v_mov_b32_e32 v52, v2
	v_mov_b32_e32 v53, v2
	v_mov_b32_e32 v58, v2
	v_mov_b32_e32 v59, v2
	v_mov_b32_e32 v60, v2
	v_mov_b32_e32 v61, v2
	v_mov_b32_e32 v6, v2
	v_mov_b32_e32 v7, v2
	v_mov_b32_e32 v8, v2
	v_mov_b32_e32 v9, v2
	v_mov_b32_e32 v14, v2
	v_mov_b32_e32 v15, v2
	v_mov_b32_e32 v16, v2
	v_mov_b32_e32 v17, v2
	v_mov_b32_e32 v22, v2
	v_mov_b32_e32 v23, v2
	v_mov_b32_e32 v24, v2
	v_mov_b32_e32 v25, v2
	v_mov_b32_e32 v30, v2
	v_mov_b32_e32 v31, v2
	v_mov_b32_e32 v32, v2
	v_mov_b32_e32 v33, v2
	v_mov_b32_e32 v38, v2
	v_mov_b32_e32 v39, v2
	v_mov_b32_e32 v40, v2
	v_mov_b32_e32 v41, v2
	v_mov_b32_e32 v46, v2
	v_mov_b32_e32 v47, v2
	v_mov_b32_e32 v48, v2
	v_mov_b32_e32 v49, v2
	v_mov_b32_e32 v54, v2
	v_mov_b32_e32 v55, v2
	v_mov_b32_e32 v56, v2
	v_mov_b32_e32 v57, v2
	v_mov_b32_e32 v62, v2
	v_mov_b32_e32 v63, v2
	v_mov_b32_e32 v64, v2
	v_mov_b32_e32 v65, v2
	v_mov_b32_e32 v66, v2
	v_mov_b32_e32 v67, v2
	v_mov_b32_e32 v68, v2
	v_mov_b32_e32 v69, v2
	v_mov_b32_e32 v74, v2
	v_mov_b32_e32 v75, v2
	v_mov_b32_e32 v76, v2
	v_mov_b32_e32 v77, v2
	v_mov_b32_e32 v82, v2
	v_mov_b32_e32 v83, v2
	v_mov_b32_e32 v84, v2
	v_mov_b32_e32 v85, v2
	v_mov_b32_e32 v90, v2
	v_mov_b32_e32 v91, v2
	v_mov_b32_e32 v92, v2
	v_mov_b32_e32 v93, v2
	v_mov_b32_e32 v98, v2
	v_mov_b32_e32 v99, v2
	v_mov_b32_e32 v100, v2
	v_mov_b32_e32 v101, v2
	v_mov_b32_e32 v106, v2
	v_mov_b32_e32 v107, v2
	v_mov_b32_e32 v108, v2
	v_mov_b32_e32 v109, v2
	v_mov_b32_e32 v114, v2
	v_mov_b32_e32 v115, v2
	v_mov_b32_e32 v116, v2
	v_mov_b32_e32 v117, v2
	v_mov_b32_e32 v122, v2
	v_mov_b32_e32 v123, v2
	v_mov_b32_e32 v124, v2
	v_mov_b32_e32 v125, v2
	v_mov_b32_e32 v70, v2
	v_mov_b32_e32 v71, v2
	v_mov_b32_e32 v72, v2
	v_mov_b32_e32 v73, v2
	v_mov_b32_e32 v78, v2
	v_mov_b32_e32 v79, v2
	v_mov_b32_e32 v80, v2
	v_mov_b32_e32 v81, v2
	v_mov_b32_e32 v86, v2
	v_mov_b32_e32 v87, v2
	v_mov_b32_e32 v88, v2
	v_mov_b32_e32 v89, v2
	v_mov_b32_e32 v94, v2
	v_mov_b32_e32 v95, v2
	v_mov_b32_e32 v96, v2
	v_mov_b32_e32 v97, v2
	v_mov_b32_e32 v102, v2
	v_mov_b32_e32 v103, v2
	v_mov_b32_e32 v104, v2
	v_mov_b32_e32 v105, v2
	v_mov_b32_e32 v110, v2
	v_mov_b32_e32 v111, v2
	v_mov_b32_e32 v112, v2
	v_mov_b32_e32 v113, v2
	v_mov_b32_e32 v118, v2
	v_mov_b32_e32 v119, v2
	v_mov_b32_e32 v120, v2
	v_mov_b32_e32 v121, v2
	v_mov_b32_e32 v126, v2
	v_mov_b32_e32 v127, v2
	v_mov_b32_e32 v128, v2
	v_mov_b32_e32 v129, v2
	.p2align	8

; #define PG8_STAGE(bufoff, gbase, voff) do { _Pragma("unroll") for (int _i = 0; _i < 2; ++_i) \
;     __builtin_amdgcn_global_load_lds((const unsigned*)((const char*)(gbase) + (voff)[_i]), (LAS unsigned*)(lds + (bufoff) + ldsw + _i * 8192), 16, 0, 0); } while (0)
; #define PG8_WAIT_V(n) asm volatile("s_waitcnt vmcnt(" #n ")" ::: "memory")
; #define PG8_BAR __builtin_amdgcn_s_barrier()
; template <class Epi, class Sched>
; DI void gemm_phase(LAS unsigned char* lds, const Gemm g, const Sched& S, const Epi& E) {
;     ...
;   f32x4 acc[2][2][4][2];
; #pragma unroll
;   for (int a = 0; a < 2; ++a)
; #pragma unroll
;     for (int b = 0; b < 2; ++b)
; #pragma unroll
;       for (int m = 0; m < 4; ++m)
; #pragma unroll
;         for (int n = 0; n < 2; ++n) acc[a][b][m][n] = (f32x4){0.f, 0.f, 0.f, 0.f};
;   bf16x8 At[4][2], B0[2][2], B1[2][2];
;   const char* cA = (const char*)g.A + (size_t)cur.pm * tstep; const char* cB = (const char*)g.Bt + (size_t)cur.pn * tstep;
;   PG8_STAGE(PG8_SB(0, 0), cB, voffB); PG8_STAGE(PG8_SA(0, 0), cA, voffA); PG8_STAGE(PG8_SB(0, 1), cB + hstepB, voffB); PG8_STAGE(PG8_SA(0, 1), cA + hstep, voffA);
;   if (wr == 1) PG8_BAR;
;   PG8_WAIT_V(4); PG8_BAR;
;   PG8_STAGE(PG8_SB(1, 0), cB + kstep, voffB); PG8_STAGE(PG8_SA(1, 0), cA + kstep, voffA); PG8_STAGE(PG8_SB(1, 1), cB + hstepB + kstep, voffB);
;   PG8_WAIT_V(6); PG8_BAR;
.LBB0_215:
	v_lshl_add_u64 v[4:5], s[12:13], 0, v[0:1]
	v_mov_b32_e32 v131, v1
	v_lshl_add_u64 v[6:7], s[12:13], 0, v[130:131]
	v_and_b32_e32 v132, 15, v2
	v_bfe_u32 v136, v2, 4, 2
	s_add_i32 m0, s30, 0x18000
	v_lshl_add_u64 v[2:3], v[4:5], 0, s[70:71]
	v_lshl_add_u64 v[8:9], s[14:15], 0, v[0:1]
	s_waitcnt vmcnt(4)
	s_barrier
	global_load_lds_dwordx4 v[2:3], off
	v_lshl_add_u64 v[2:3], v[6:7], 0, s[70:71]
	s_add_i32 m0, s30, 0x1a000
	s_add_i32 s36, s30, 0x8000
	v_lshl_add_u64 v[10:11], s[14:15], 0, v[130:131]
	global_load_lds_dwordx4 v[2:3], off
	v_lshl_add_u64 v[2:3], v[8:9], 0, s[70:71]
	s_mov_b32 m0, s36
	s_add_i32 s37, s30, 0xa000
	v_lshl_add_u64 v[12:13], s[18:19], 0, v[0:1]
	global_load_lds_dwordx4 v[2:3], off
	v_lshl_add_u64 v[2:3], v[10:11], 0, s[70:71]
	s_mov_b32 m0, s37
	v_lshl_add_u64 v[14:15], s[18:19], 0, v[130:131]
	global_load_lds_dwordx4 v[2:3], off
	s_add_i32 m0, s30, 0x1c000
	v_lshl_add_u64 v[2:3], v[12:13], 0, s[70:71]
	global_load_lds_dwordx4 v[2:3], off
	v_lshl_add_u64 v[2:3], v[14:15], 0, s[70:71]
	s_add_i32 m0, s30, 0x1e000
	s_lshl_b32 s18, s21, 5
	global_load_lds_dwordx4 v[2:3], off
	s_waitcnt vmcnt(6)
	s_and_b32 s27, s18, 0x60
	v_mov_b32_e32 v129, 0
	v_lshl_or_b32 v146, s20, 6, v132
	s_cmp_lt_i32 s16, 64
	v_mov_b32_e32 v128, v129
	v_mov_b32_e32 v127, v129
	v_mov_b32_e32 v126, v129
	v_mov_b32_e32 v125, v129
	v_mov_b32_e32 v124, v129
	v_mov_b32_e32 v123, v129
	v_mov_b32_e32 v122, v129
	v_mov_b32_e32 v113, v129
	v_mov_b32_e32 v112, v129
	v_mov_b32_e32 v111, v129
	v_mov_b32_e32 v110, v129
	v_mov_b32_e32 v109, v129
	v_mov_b32_e32 v108, v129
	v_mov_b32_e32 v107, v129
	v_mov_b32_e32 v106, v129
	v_mov_b32_e32 v97, v129
	v_mov_b32_e32 v96, v129
	v_mov_b32_e32 v95, v129
	v_mov_b32_e32 v94, v129
	v_mov_b32_e32 v93, v129
	v_mov_b32_e32 v92, v129
	v_mov_b32_e32 v91, v129
	v_mov_b32_e32 v90, v129
	v_mov_b32_e32 v81, v129
	v_mov_b32_e32 v80, v129
	v_mov_b32_e32 v79, v129
	v_mov_b32_e32 v78, v129
	v_mov_b32_e32 v77, v129
	v_mov_b32_e32 v76, v129
	v_mov_b32_e32 v75, v129
	v_mov_b32_e32 v74, v129
	v_mov_b32_e32 v121, v129
	v_mov_b32_e32 v120, v129
	v_mov_b32_e32 v119, v129
	v_mov_b32_e32 v118, v129
	v_mov_b32_e32 v117, v129
	v_mov_b32_e32 v116, v129
	v_mov_b32_e32 v115, v129
	v_mov_b32_e32 v114, v129
	v_mov_b32_e32 v105, v129
	v_mov_b32_e32 v104, v129
	v_mov_b32_e32 v103, v129
	v_mov_b32_e32 v102, v129
	v_mov_b32_e32 v101, v129
	v_mov_b32_e32 v100, v129
	v_mov_b32_e32 v99, v129
	v_mov_b32_e32 v98, v129
	v_mov_b32_e32 v89, v129
	v_mov_b32_e32 v88, v129
	v_mov_b32_e32 v87, v129
	v_mov_b32_e32 v86, v129
	v_mov_b32_e32 v85, v129
	v_mov_b32_e32 v84, v129
	v_mov_b32_e32 v83, v129
	v_mov_b32_e32 v82, v129
	v_mov_b32_e32 v73, v129
	v_mov_b32_e32 v72, v129
	v_mov_b32_e32 v71, v129
	v_mov_b32_e32 v70, v129
	v_mov_b32_e32 v69, v129
	v_mov_b32_e32 v68, v129
	v_mov_b32_e32 v67, v129
	v_mov_b32_e32 v66, v129
	v_mov_b32_e32 v65, v129
	v_mov_b32_e32 v64, v129
	v_mov_b32_e32 v63, v129
	v_mov_b32_e32 v62, v129
	v_mov_b32_e32 v61, v129
	v_mov_b32_e32 v60, v129
	v_mov_b32_e32 v59, v129
	v_mov_b32_e32 v58, v129
	v_mov_b32_e32 v53, v129
	v_mov_b32_e32 v52, v129
	v_mov_b32_e32 v51, v129
	v_mov_b32_e32 v50, v129
	v_mov_b32_e32 v45, v129
	v_mov_b32_e32 v44, v129
	v_mov_b32_e32 v43, v129
	v_mov_b32_e32 v42, v129
	v_mov_b32_e32 v37, v129
	v_mov_b32_e32 v36, v129
	v_mov_b32_e32 v35, v129
	v_mov_b32_e32 v34, v129
	v_mov_b32_e32 v29, v129
	v_mov_b32_e32 v28, v129
	v_mov_b32_e32 v27, v129
	v_mov_b32_e32 v26, v129
	v_mov_b32_e32 v17, v129
	v_mov_b32_e32 v16, v129
	v_mov_b32_e32 v15, v129
	v_mov_b32_e32 v14, v129
	v_mov_b32_e32 v13, v129
	v_mov_b32_e32 v12, v129
	v_mov_b32_e32 v11, v129
	v_mov_b32_e32 v10, v129
	v_mov_b32_e32 v57, v129
	v_mov_b32_e32 v56, v129
	v_mov_b32_e32 v55, v129
	v_mov_b32_e32 v54, v129
	v_mov_b32_e32 v49, v129
	v_mov_b32_e32 v48, v129
	v_mov_b32_e32 v47, v129
	v_mov_b32_e32 v46, v129
	v_mov_b32_e32 v41, v129
	v_mov_b32_e32 v40, v129
	v_mov_b32_e32 v39, v129
	v_mov_b32_e32 v38, v129
	v_mov_b32_e32 v33, v129
	v_mov_b32_e32 v32, v129
	v_mov_b32_e32 v31, v129
	v_mov_b32_e32 v30, v129
	v_mov_b32_e32 v25, v129
	v_mov_b32_e32 v24, v129
	v_mov_b32_e32 v23, v129
	v_mov_b32_e32 v22, v129
	v_mov_b32_e32 v21, v129
	v_mov_b32_e32 v20, v129
	v_mov_b32_e32 v19, v129
	v_mov_b32_e32 v18, v129
	v_mov_b32_e32 v9, v129
	v_mov_b32_e32 v8, v129
	v_mov_b32_e32 v7, v129
	v_mov_b32_e32 v6, v129
	v_mov_b32_e32 v5, v129
	v_mov_b32_e32 v4, v129
	v_mov_b32_e32 v3, v129
	v_mov_b32_e32 v2, v129
	s_barrier
; template <class Epi, class Sched>
; DI void gemm_phase(LAS unsigned char* lds, const Gemm g, const Sched& S, const Epi& E) {
;     ...
;   const int nt = K / BK;
;   unsigned voffA[2], voffB[2];
; #pragma unroll
;   for (int i = 0; i < 2; ++i) {
;     int R, C; stage_rc(tid * 16 + i * 8192, R, C);
;     int Rb = R;
;     if (Epi::BMAP == 1) Rb = (R & ~31) + perm32(R & 31);
;     if (Epi::BMAP == 2) Rb = 64 * (R >> 5) + perm32(R & 31);
;     voffA[i] = (unsigned)(R * K + C) * 2u; voffB[i] = (unsigned)(Rb * K + C) * 2u;
;   }
;   const size_t kstep = (size_t)(BK * 2);
;   const size_t hstep = (size_t)HALF * K * 2;
;   const size_t hstepB = (Epi::BMAP == 2) ? (size_t)32 * K * 2 : hstep;
;   const size_t tstep = 2 * hstep;
;   const unsigned ldsw = (unsigned)wid * 1024u;
;   const int aoff = lds_byte(wr * 64 + fr, fq * 8), boff = lds_byte(wc * 32 + fr, fq * 8);
;     ...
; #pragma unroll
;   for (int a = 0; a < 2; ++a)
; #pragma unroll
;     for (int b = 0; b < 2; ++b)
; #pragma unroll
;       for (int m = 0; m < 4; ++m)
; #pragma unroll
;         for (int n = 0; n < 2; ++n) acc[a][b][m][n] = (f32x4){0.f, 0.f, 0.f, 0.f};
	s_cbranch_scc1 .LBB0_218
	s_lshr_b32 s18, s17, 26
	s_add_i32 s18, s16, s18
	s_ashr_i32 s38, s18, 6
	v_lshlrev_b32_e32 v2, 4, v136
	v_lshlrev_b32_e32 v3, 6, v146
	s_movk_i32 s18, 0x3c0
	v_lshlrev_b32_e32 v4, 2, v146
	v_and_or_b32 v3, v3, s18, v2
	s_lshl_b32 s18, s20, 13
	v_and_b32_e32 v4, 32, v4
	v_bitop3_b32 v3, v3, s18, v4 bitop3:0xde
	v_lshlrev_b32_e32 v4, 2, v132
	v_lshl_or_b32 v2, v132, 6, v2
	s_lshl_b32 s18, s27, 7
	v_and_b32_e32 v4, 32, v4
	v_bitop3_b32 v137, v2, s18, v4 bitop3:0xde
	s_lshl_b64 s[18:19], s[2:3], 9
	s_or_b32 s3, s18, 0x100
	s_mul_i32 s17, s3, s17
	s_mul_hi_u32 s18, s3, s16
	s_add_i32 s17, s18, s17
	s_mul_i32 s18, s19, s16
	s_add_i32 s39, s38, -2
	s_add_i32 s17, s17, s18
	s_mul_i32 s3, s3, s16
	s_add_u32 s16, s90, s3
	s_addc_u32 s17, s91, s17
	v_mov_b32_e32 v2, 0
	v_lshl_add_u64 v[132:133], s[16:17], 0, v[0:1]
	v_lshl_add_u64 v[134:135], s[16:17], 0, v[130:131]
	s_mov_b32 s3, 0
	s_mov_b64 s[16:17], 0x80
	v_add_u32_e32 v138, 16, v3
	v_mov_b32_e32 v3, v2
	v_mov_b32_e32 v4, v2
	v_mov_b32_e32 v5, v2
	v_mov_b32_e32 v6, v2
	v_mov_b32_e32 v7, v2
	v_mov_b32_e32 v8, v2
	v_mov_b32_e32 v9, v2
	v_mov_b32_e32 v18, v2
	v_mov_b32_e32 v19, v2
	v_mov_b32_e32 v20, v2
	v_mov_b32_e32 v21, v2
	v_mov_b32_e32 v22, v2
	v_mov_b32_e32 v23, v2
	v_mov_b32_e32 v24, v2
	v_mov_b32_e32 v25, v2
	v_mov_b32_e32 v30, v2
	v_mov_b32_e32 v31, v2
	v_mov_b32_e32 v32, v2
	v_mov_b32_e32 v33, v2
	v_mov_b32_e32 v38, v2
	v_mov_b32_e32 v39, v2
	v_mov_b32_e32 v40, v2
	v_mov_b32_e32 v41, v2
	v_mov_b32_e32 v46, v2
	v_mov_b32_e32 v47, v2
	v_mov_b32_e32 v48, v2
	v_mov_b32_e32 v49, v2
	v_mov_b32_e32 v54, v2
	v_mov_b32_e32 v55, v2
	v_mov_b32_e32 v56, v2
	v_mov_b32_e32 v57, v2
	v_mov_b32_e32 v10, v2
	v_mov_b32_e32 v11, v2
	v_mov_b32_e32 v12, v2
	v_mov_b32_e32 v13, v2
	v_mov_b32_e32 v14, v2
	v_mov_b32_e32 v15, v2
	v_mov_b32_e32 v16, v2
	v_mov_b32_e32 v17, v2
	v_mov_b32_e32 v26, v2
	v_mov_b32_e32 v27, v2
	v_mov_b32_e32 v28, v2
	v_mov_b32_e32 v29, v2
	v_mov_b32_e32 v34, v2
	v_mov_b32_e32 v35, v2
	v_mov_b32_e32 v36, v2
	v_mov_b32_e32 v37, v2
	v_mov_b32_e32 v42, v2
	v_mov_b32_e32 v43, v2
	v_mov_b32_e32 v44, v2
	v_mov_b32_e32 v45, v2
	v_mov_b32_e32 v50, v2
	v_mov_b32_e32 v51, v2
	v_mov_b32_e32 v52, v2
	v_mov_b32_e32 v53, v2
	v_mov_b32_e32 v58, v2
	v_mov_b32_e32 v59, v2
	v_mov_b32_e32 v60, v2
	v_mov_b32_e32 v61, v2
	v_mov_b32_e32 v62, v2
	v_mov_b32_e32 v63, v2
	v_mov_b32_e32 v64, v2
	v_mov_b32_e32 v65, v2
	v_mov_b32_e32 v66, v2
	v_mov_b32_e32 v67, v2
	v_mov_b32_e32 v68, v2
	v_mov_b32_e32 v69, v2
	v_mov_b32_e32 v70, v2
	v_mov_b32_e32 v71, v2
	v_mov_b32_e32 v72, v2
	v_mov_b32_e32 v73, v2
	v_mov_b32_e32 v82, v2
	v_mov_b32_e32 v83, v2
	v_mov_b32_e32 v84, v2
	v_mov_b32_e32 v85, v2
	v_mov_b32_e32 v86, v2
	v_mov_b32_e32 v87, v2
	v_mov_b32_e32 v88, v2
	v_mov_b32_e32 v89, v2
	v_mov_b32_e32 v98, v2
	v_mov_b32_e32 v99, v2
	v_mov_b32_e32 v100, v2
	v_mov_b32_e32 v101, v2
	v_mov_b32_e32 v102, v2
	v_mov_b32_e32 v103, v2
	v_mov_b32_e32 v104, v2
	v_mov_b32_e32 v105, v2
	v_mov_b32_e32 v114, v2
	v_mov_b32_e32 v115, v2
	v_mov_b32_e32 v116, v2
	v_mov_b32_e32 v117, v2
	v_mov_b32_e32 v118, v2
	v_mov_b32_e32 v119, v2
	v_mov_b32_e32 v120, v2
	v_mov_b32_e32 v121, v2
	v_mov_b32_e32 v74, v2
	v_mov_b32_e32 v75, v2
	v_mov_b32_e32 v76, v2
	v_mov_b32_e32 v77, v2
	v_mov_b32_e32 v78, v2
	v_mov_b32_e32 v79, v2
	v_mov_b32_e32 v80, v2
	v_mov_b32_e32 v81, v2
	v_mov_b32_e32 v90, v2
	v_mov_b32_e32 v91, v2
	v_mov_b32_e32 v92, v2
	v_mov_b32_e32 v93, v2
	v_mov_b32_e32 v94, v2
	v_mov_b32_e32 v95, v2
	v_mov_b32_e32 v96, v2
	v_mov_b32_e32 v97, v2
	v_mov_b32_e32 v106, v2
	v_mov_b32_e32 v107, v2
	v_mov_b32_e32 v108, v2
	v_mov_b32_e32 v109, v2
	v_mov_b32_e32 v110, v2
	v_mov_b32_e32 v111, v2
	v_mov_b32_e32 v112, v2
	v_mov_b32_e32 v113, v2
	v_mov_b32_e32 v122, v2
	v_mov_b32_e32 v123, v2
	v_mov_b32_e32 v124, v2
	v_mov_b32_e32 v125, v2
	v_mov_b32_e32 v126, v2
	v_mov_b32_e32 v127, v2
	v_mov_b32_e32 v128, v2
	v_mov_b32_e32 v129, v2
	.p2align	8

; DI void attn_item(const Params& p, int layer, int item, char* smem) {
;     ...
;   if (mode == 0) { qchunk = 22 + hh; kchunk = 28 + hh / 3; vchunk = 30 + hh / 3; head16 = 10 + hh; t0 = 0; t1 = 64; }
;   else if (mode == 1) {
;     qchunk = 10 + hh; kchunk = 14 + hh; vchunk = 18 + hh; head16 = 6 + hh; maskmode = 1;
;     t0 = min(max(4 * qb - 4, 0), 56); t1 = min(max(4 * qb + 3 - 4, 0), 56) + 8;
;   } else if (mode == 2) {
;     qchunk = hh; kchunk = 6 + hh / 3; vchunk = 8 + hh / 3; head16 = hh; maskmode = 2;
;     t0 = max(0, 4 * qb - 2); t1 = min(64, 4 * qb + 6); hasSink = true; sinkv = p.sink[layer * 6 + hh];
;   } else {
;     head16 = hh; qpos0 = 4096;
;     if (hh < 6) { qchunk = hh; kchunk = 6 + hh / 3; vchunk = 8 + hh / 3; hasSink = true; sinkv = p.sink[layer * 6 + hh]; }
;     else if (hh < 10) { int hb = hh - 6; qchunk = 10 + hb; kchunk = 14 + hb; vchunk = 18 + hb; }
;     else { int hc = hh - 10; qchunk = 22 + hc; kchunk = 28 + hc / 3; vchunk = 30 + hc / 3; }
;   }
;   const int n_it = 4 + (t1 - t0);
;   const u16* Qb = p.QKV + (size_t)(b * 32 + qchunk) * LTOT * 64;
;   const u16* Kb = p.QKV + (size_t)(b * 32 + kchunk) * LTOT * 64;
;   const u16* Vb = p.QKV + (size_t)(b * 32 + vchunk) * LTOT * 64;
;   float* s_rpb = (float*)(smem + RPB_OFF);
;   if (mode == 1) {
;     const float* rp = p.rpb + (size_t)(layer * 4 + hh) * 465;
;     for (int e = tid; e < 465; e += NTHR) s_rpb[e] = rp[e] * LOG2E;
;   }
;   const int qpos = qpos0 + wid * 32 + l32;
;   bf16x8 qf[4];
; #pragma unroll
;   for (int s = 0; s < 4; ++s) qf[s] = *(const bf16x8*)(Qb + (size_t)qpos * 64 + s * 16 + h * 8);
;   f32x16 o0, o1;
; #pragma unroll
;   for (int r = 0; r < 16; ++r) { o0[r] = 0.f; o1[r] = 0.f; }
;   const int btype = (mode == 3) ? (hh < 6 ? 0 : (hh < 10 ? 1 : 2)) : (mode == 0 ? 2 : (mode == 1 ? 1 : 0));
;   float m_fix = p.bounds[layer * 8 + btype];
;   if (mode == 1) m_fix += p.bounds[layer * 8 + 4 + hh];
;   f32x16 cinit, lacc;
; #pragma unroll
;   for (int r = 0; r < 16; ++r) { cinit[r] = -m_fix; lacc[r] = 0.f; }
;     ...
;   AGLOAD(ka0, va0, TILE_OF(0));
;   if (n_it > 1) { AGLOAD(kb0, vb0, TILE_OF(1)); }
;   ASWRITE(ka0, va0, 0);
;   if (n_it > 2) { AGLOAD(ka0, va0, TILE_OF(2)); }
;   __syncthreads();
.LBB0_259:
	s_mul_hi_i32 s0, s14, 0x2aaaaaab
	s_lshr_b32 s1, s0, 31
	s_ashr_i32 s5, s0, 4
	s_add_i32 s5, s5, s1
	s_mul_i32 s0, s5, 0x60
	s_sub_i32 s0, s14, s0
	v_mov_b32_e32 v32, v213
	s_ashr_i32 s4, s0, 4
	s_lshl_b32 s0, s0, 8
	s_and_b32 s8, s0, 0xf00
	s_lshl_b32 s0, s5, 5
	v_ashrrev_i32_e32 v0, 1, v32
	s_add_i32 s1, s4, s0
	s_mul_i32 s2, s4, 0x56
	v_and_b32_e32 v0, 0xffffffe0, v0
	v_and_b32_e32 v36, 31, v32
	s_bfe_u32 s3, s2, 0x1000f
	s_bfe_u32 s2, s2, 0x80008
	s_add_i32 s1, s1, 22
	v_add_u32_e32 v0, s8, v0
	s_add_i32 s2, s2, s3
	s_mul_hi_i32 s3, s1, 0x88000
	s_mul_i32 s1, s1, 0x88000
	v_or_b32_e32 v134, v0, v36
	s_add_u32 s6, s88, s1
	v_ashrrev_i32_e32 v135, 31, v134
	v_bfe_u32 v140, v32, 5, 1
	s_addc_u32 s7, s89, s3
	v_lshlrev_b64 v[2:3], 7, v[134:135]
	v_lshl_add_u64 v[2:3], s[6:7], 0, v[2:3]
	v_lshlrev_b32_e32 v18, 4, v140
	v_mov_b32_e32 v19, v1
	v_readlane_b32 s6, v254, 50
	v_lshl_add_u64 v[2:3], v[2:3], 0, v[18:19]
	v_readlane_b32 s7, v254, 51
	global_load_dwordx4 v[98:101], v[2:3], off
	global_load_dwordx4 v[102:105], v[2:3], off offset:32
	global_load_dwordx4 v[106:109], v[2:3], off offset:64
	global_load_dwordx4 v[110:113], v[2:3], off offset:96
	s_sext_i32_i8 s2, s2
	global_load_dword v2, v1, s[6:7] offset:8
	s_add_i32 s2, s0, s2
	s_mul_i32 s3, s2, 0x88000
	s_add_i32 s0, s2, 28
	s_mul_hi_i32 s1, s0, 0x88000
	s_add_i32 s0, s3, 0xee0000
	v_ashrrev_i32_e32 v30, 3, v32
	s_add_u32 s0, s88, s0
	v_ashrrev_i32_e32 v31, 31, v30
	s_addc_u32 s1, s89, s1
	v_lshlrev_b32_e32 v19, 4, v32
	v_lshlrev_b64 v[20:21], 7, v[30:31]
	v_lshl_add_u64 v[136:137], s[0:1], 0, v[20:21]
	s_mov_b32 s6, 0x80000
	s_add_i32 s2, s2, 30
	s_add_i32 s3, s3, 0xff0000
	s_mul_hi_i32 s9, s2, 0x88000
	s_add_u32 s2, s88, s3
	s_addc_u32 s3, s89, s9
	v_mov_b64_e32 v[26:27], s[2:3]
	v_mad_i64_i32 v[138:139], s[2:3], v30, s28, v[26:27]
	s_movk_i32 s3, 0x90
	s_mov_b32 s2, 0x82000
	v_mul_lo_u32 v30, v30, s3
	v_add_u32_e32 v30, 16, v30
	v_add_u32_e32 v144, 16, v18
	v_mul_u32_u24_e32 v145, 0x90, v36
	v_mad_u32_u24 v146, v36, s3, v144
	v_and_b32_e32 v0, 0x70, v19
	v_lshl_add_u64 v[34:35], v[136:137], 0, v[0:1]
	v_add_co_u32_e32 v22, vcc, s6, v34
	v_add_u32_e32 v135, v30, v0
	s_nop 0
	v_addc_co_u32_e32 v23, vcc, 0, v35, vcc
	global_load_dwordx4 v[22:25], v[22:23], off
	v_add_co_u32_e32 v26, vcc, s2, v34
	v_lshl_add_u64 v[74:75], v[138:139], 0, v[0:1]
	s_nop 0
	v_addc_co_u32_e32 v27, vcc, 0, v35, vcc
	global_load_dwordx4 v[26:29], v[26:27], off
	s_movk_i32 s2, 0x2000
	v_lshlrev_b32_e32 v78, 3, v32
	v_and_b32_e32 v78, 8, v78
	v_and_or_b32 v19, v19, s74, v78
	v_add_co_u32_e32 v78, vcc, s2, v74
	v_add_u32_e32 v19, v30, v19
	s_nop 0
	v_addc_co_u32_e32 v79, vcc, 0, v75, vcc
	global_load_dwordx4 v[30:33], v[78:79], off
	s_mov_b32 s2, 0x84000
	v_add_co_u32_e32 v80, vcc, s2, v34
	v_add_u32_e32 v141, 0x2000, v19
	s_nop 0
	v_addc_co_u32_e32 v81, vcc, 0, v35, vcc
	global_load_dwordx4 v[66:69], v[80:81], off
	global_load_dwordx4 v[70:73], v[78:79], off offset:256
	v_lshl_add_u64 v[80:81], s[0:1], 0, v[0:1]
	v_lshl_add_u64 v[76:77], v[80:81], 0, v[20:21]
	s_mov_b32 s0, 0x86000
	v_add_u32_e32 v143, 0x6800, v19
	s_waitcnt vmcnt(5)
	v_xor_b32_e32 v2, 0x80000000, v2
	v_mov_b32_e32 v3, v2
	v_mov_b32_e32 v4, v2
	v_mov_b32_e32 v5, v2
	v_mov_b32_e32 v6, v2
	v_mov_b32_e32 v7, v2
	v_mov_b32_e32 v8, v2
	v_mov_b32_e32 v9, v2
	v_mov_b32_e32 v10, v2
	v_mov_b32_e32 v11, v2
	v_mov_b32_e32 v12, v2
	v_mov_b32_e32 v13, v2
	v_mov_b32_e32 v14, v2
	v_mov_b32_e32 v15, v2
	v_mov_b32_e32 v16, v2
	v_mov_b32_e32 v17, v2
	s_waitcnt vmcnt(4)
	ds_write_b128 v135, v[22:25]
	s_waitcnt vmcnt(2)
	ds_write2_b64 v141, v[30:31], v[32:33] offset0:128 offset1:130
	v_mad_u32_u24 v30, v36, s3, 16
	v_add_u32_e32 v142, v30, v18
	global_load_dwordx4 v[30:33], v[78:79], off offset:128
	v_add_co_u32_e32 v18, vcc, s0, v76
	s_waitcnt lgkmcnt(0)
	s_barrier
	ds_write_b128 v135, v[26:29] offset:18432
	v_addc_co_u32_e32 v19, vcc, 0, v77, vcc
	s_waitcnt vmcnt(0)
	ds_write2_b64 v143, v[30:31], v[32:33] offset0:128 offset1:130
	global_load_dwordx4 v[114:117], v[18:19], off
	global_load_dwordx4 v[118:121], v[78:79], off offset:384
	ds_read_b128 v[34:37], v146
	ds_read_b128 v[38:41], v146 offset:32
	v_mov_b64_e32 v[132:133], s[94:95]
	v_mov_b64_e32 v[130:131], s[92:93]
	s_waitcnt lgkmcnt(1)
	v_mfma_f32_32x32x16_bf16 v[18:33], v[34:37], v[98:101], v[2:17]
	ds_read_b128 v[34:37], v146 offset:64
	ds_read_b128 v[50:53], v146 offset:4608
	s_waitcnt lgkmcnt(2)
	v_mfma_f32_32x32x16_bf16 v[18:33], v[38:41], v[102:105], v[18:33]
	s_waitcnt lgkmcnt(1)
	v_mfma_f32_32x32x16_bf16 v[18:33], v[34:37], v[106:109], v[18:33]
	ds_read_b128 v[34:37], v146 offset:96
	s_waitcnt lgkmcnt(0)
	v_mfma_f32_32x32x16_bf16 v[18:33], v[34:37], v[110:113], v[18:33]
	v_mfma_f32_32x32x16_bf16 v[34:49], v[50:53], v[98:101], v[2:17]
	ds_read_b128 v[50:53], v146 offset:4640
	s_nop 9
	v_exp_f32_e32 v18, v18
	v_exp_f32_e32 v19, v19
	v_exp_f32_e32 v20, v20
	v_exp_f32_e32 v21, v21
	v_exp_f32_e32 v22, v22
	v_exp_f32_e32 v23, v23
	s_waitcnt lgkmcnt(0)
	v_mfma_f32_32x32x16_bf16 v[34:49], v[50:53], v[102:105], v[34:49]
	ds_read_b128 v[50:53], v146 offset:4672
	v_exp_f32_e32 v24, v24
	v_exp_f32_e32 v25, v25
	v_cvt_pk_bf16_f32 v18, v18, v19
	v_cvt_pk_bf16_f32 v19, v20, v21
	v_cvt_pk_bf16_f32 v20, v22, v23
	v_cvt_pk_bf16_f32 v21, v24, v25
	s_waitcnt lgkmcnt(0)
	v_mfma_f32_32x32x16_bf16 v[34:49], v[50:53], v[106:109], v[34:49]
	ds_read_b128 v[50:53], v146 offset:4704
	ds_read_b128 v[22:25], v142 offset:9216
	ds_read_b128 v[78:81], v142 offset:9248
	v_exp_f32_e32 v82, v26
	v_exp_f32_e32 v83, v27
	v_exp_f32_e32 v84, v28
	v_exp_f32_e32 v85, v29
	v_exp_f32_e32 v122, v30
	s_waitcnt lgkmcnt(2)
; DI void attn_item(const Params& p, int layer, int item, char* smem) {
;     ...
;       f32x16 S[2];
; #pragma unroll
;       for (int kt = 0; kt < 2; ++kt) {
; #pragma unroll
;         for (int s = 0; s < 4; ++s) {
;           bf16x8 kf = *(const bf16x8*)(sK + (kt * 32 + l32) * KROW + s * 32 + h * 16);
;           S[kt] = MFMA32(kf, qf[s], s == 0 ? cinit : S[kt]);
;         }
;       }
;       if (tile < 64 && maskmode == 1) {
;         int qr = tq >> 6, qc = tq & 63;
;         int ws = min(max(qc - 8, 0), 48);
;         int dr = tile - qr + 7;
; #pragma unroll
;         for (int kt = 0; kt < 2; ++kt)
; #pragma unroll
;           for (int r = 0; r < 16; ++r) {
;             int kc = kt * 32 + crow(r, h);
;             bool ok = (unsigned)(kc - ws) < 16u;
;             int bi = ok ? (dr * 31 + kc - qc + 15) : 0;
;             float bv = s_rpb[bi];
;             S[kt][r] = ok ? (S[kt][r] + bv) : -INFINITY;
;           }
;       } else if (tile < 64 && maskmode == 2) {
; #pragma unroll
;         for (int kt = 0; kt < 2; ++kt)
; #pragma unroll
;           for (int r = 0; r < 16; ++r) {
;             int tk = tile * 64 + kt * 32 + crow(r, h);
;             int dd = tq - tk;
;             bool ok = (dd <= 128) && (dd >= -128);
;             S[kt][r] = ok ? S[kt][r] : -INFINITY;
;           }
;       }
; #pragma unroll
;       for (int r = 0; r < 16; ++r) {
;         S[0][r] = __builtin_amdgcn_exp2f(S[0][r]);
;         S[1][r] = __builtin_amdgcn_exp2f(S[1][r]);
;       }
; #pragma unroll
;       for (int kt = 0; kt < 2; ++kt)
; #pragma unroll
;         for (int s2 = 0; s2 < 2; ++s2) {
;           uint4 pw;
;           pw.x = pack_bf16(S[kt][8 * s2 + 0], S[kt][8 * s2 + 1]);
;           pw.y = pack_bf16(S[kt][8 * s2 + 2], S[kt][8 * s2 + 3]);
;           pw.z = pack_bf16(S[kt][8 * s2 + 4], S[kt][8 * s2 + 5]);
;           pw.w = pack_bf16(S[kt][8 * s2 + 6], S[kt][8 * s2 + 7]);
;           bf16x8 pf = __builtin_bit_cast(bf16x8, pw);
;           const int koff = (kt * 32 + 16 * s2 + 8 * h) * 2;
;           {
;             bf16x8 vf = *(const bf16x8*)(sV + l32 * VROW + koff);
;             o0 = MFMA32(vf, pf, o0);
;             lacc = MFMA32(ones, pf, lacc);
;           }
;           {
;             bf16x8 vf = *(const bf16x8*)(sV + (32 + l32) * VROW + koff);
;             o1 = MFMA32(vf, pf, o1);
;           }
;         }
	v_mfma_f32_32x32x16_bf16 v[34:49], v[50:53], v[110:113], v[34:49]
	v_exp_f32_e32 v124, v31
	v_exp_f32_e32 v126, v32
	v_exp_f32_e32 v128, v33
	v_cvt_pk_bf16_f32 v82, v82, v83
	v_cvt_pk_bf16_f32 v83, v84, v85
	v_cvt_pk_bf16_f32 v84, v122, v124
	v_cvt_pk_bf16_f32 v85, v126, v128
	s_nop 4
	v_exp_f32_e32 v86, v34
	v_exp_f32_e32 v87, v35
	v_exp_f32_e32 v88, v36
	v_exp_f32_e32 v89, v37
	v_exp_f32_e32 v90, v38
	v_exp_f32_e32 v91, v39
	v_exp_f32_e32 v92, v40
	v_exp_f32_e32 v93, v41
	v_exp_f32_e32 v94, v42
	v_exp_f32_e32 v95, v43
	v_exp_f32_e32 v96, v44
	v_exp_f32_e32 v97, v45
	v_exp_f32_e32 v123, v46
	v_exp_f32_e32 v125, v47
	v_exp_f32_e32 v127, v48
	v_exp_f32_e32 v129, v49
	s_waitcnt lgkmcnt(1)
	v_mfma_f32_32x32x16_bf16 v[34:49], v[22:25], v[18:21], 0
	ds_read_b128 v[22:25], v142 offset:13824
	s_waitcnt lgkmcnt(1)
	v_mfma_f32_32x32x16_bf16 v[34:49], v[78:81], v[82:85], v[34:49]
	ds_read_b128 v[78:81], v142 offset:13856
	v_mfma_f32_32x32x16_bf16 v[50:65], v[130:133], v[18:21], 0
	s_waitcnt lgkmcnt(1)
	v_mfma_f32_32x32x16_bf16 v[18:33], v[22:25], v[18:21], 0
	v_mfma_f32_32x32x16_bf16 v[50:65], v[130:133], v[82:85], v[50:65]
	s_waitcnt lgkmcnt(0)
	v_mfma_f32_32x32x16_bf16 v[18:33], v[78:81], v[82:85], v[18:33]
	ds_read_b128 v[82:85], v142 offset:9280
	v_cvt_pk_bf16_f32 v78, v86, v87
	v_cvt_pk_bf16_f32 v79, v88, v89
	v_cvt_pk_bf16_f32 v80, v90, v91
	v_cvt_pk_bf16_f32 v81, v92, v93
	s_waitcnt lgkmcnt(0)
	s_nop 0
	v_mfma_f32_32x32x16_bf16 v[34:49], v[82:85], v[78:81], v[34:49]
	ds_read_b128 v[82:85], v142 offset:13888
	s_waitcnt lgkmcnt(0)
	v_mfma_f32_32x32x16_bf16 v[18:33], v[82:85], v[78:81], v[18:33]
	ds_read_b128 v[82:85], v142 offset:9312
	v_mfma_f32_32x32x16_bf16 v[50:65], v[130:133], v[78:81], v[50:65]
	v_cvt_pk_bf16_f32 v78, v94, v95
	v_cvt_pk_bf16_f32 v79, v96, v97
	v_cvt_pk_bf16_f32 v80, v123, v125
	v_cvt_pk_bf16_f32 v81, v127, v129
	s_waitcnt lgkmcnt(0)
	s_nop 0
	v_mfma_f32_32x32x16_bf16 v[34:49], v[82:85], v[78:81], v[34:49]
	ds_read_b128 v[82:85], v142 offset:13920
	s_waitcnt lgkmcnt(0)
	s_barrier
	ds_write_b128 v135, v[66:69]
	ds_write2_b64 v141, v[70:71], v[72:73] offset0:128 offset1:130
	global_load_dwordx4 v[122:125], v[76:77], off
	global_load_dwordx4 v[126:129], v[74:75], off
	v_mfma_f32_32x32x16_bf16 v[50:65], v[130:133], v[78:81], v[50:65]
	v_mfma_f32_32x32x16_bf16 v[18:33], v[82:85], v[78:81], v[18:33]
	ds_read_b128 v[82:85], v146 offset:18432
	ds_read_b128 v[86:89], v146 offset:18464
	s_mov_b32 s2, 2
	v_add_u32_e32 v144, v144, v145
	s_waitcnt lgkmcnt(1)
	v_mfma_f32_32x32x16_bf16 v[66:81], v[82:85], v[98:101], v[2:17]
	ds_read_b128 v[82:85], v146 offset:18496
	ds_read_b128 v[148:151], v146 offset:23040
	s_waitcnt lgkmcnt(2)
	v_mfma_f32_32x32x16_bf16 v[66:81], v[86:89], v[102:105], v[66:81]
	s_waitcnt lgkmcnt(1)
	v_mfma_f32_32x32x16_bf16 v[66:81], v[82:85], v[106:109], v[66:81]
	ds_read_b128 v[82:85], v146 offset:18528
	s_waitcnt lgkmcnt(0)
	v_mfma_f32_32x32x16_bf16 v[66:81], v[82:85], v[110:113], v[66:81]
	v_mfma_f32_32x32x16_bf16 v[82:97], v[148:151], v[98:101], v[2:17]
	ds_read_b128 v[148:151], v146 offset:23072
	s_nop 9
	v_exp_f32_e32 v66, v66
	v_exp_f32_e32 v67, v67
	v_exp_f32_e32 v68, v68
	v_exp_f32_e32 v69, v69
	v_exp_f32_e32 v70, v70
	v_exp_f32_e32 v71, v71
	s_waitcnt lgkmcnt(0)
	v_mfma_f32_32x32x16_bf16 v[82:97], v[148:151], v[102:105], v[82:97]
	ds_read_b128 v[148:151], v146 offset:23104
	v_exp_f32_e32 v72, v72
	v_exp_f32_e32 v73, v73
	v_cvt_pk_bf16_f32 v66, v66, v67
	v_cvt_pk_bf16_f32 v67, v68, v69
	v_cvt_pk_bf16_f32 v68, v70, v71
	v_cvt_pk_bf16_f32 v69, v72, v73
	s_waitcnt lgkmcnt(0)
	v_mfma_f32_32x32x16_bf16 v[82:97], v[148:151], v[106:109], v[82:97]
	ds_read_b128 v[146:149], v146 offset:23136
	v_exp_f32_e32 v78, v78
	v_exp_f32_e32 v79, v79
	v_exp_f32_e32 v80, v80
	v_exp_f32_e32 v81, v81
	s_waitcnt lgkmcnt(0)
	v_mfma_f32_32x32x16_bf16 v[82:97], v[146:149], v[110:113], v[82:97]
	v_exp_f32_e32 v146, v74
	v_exp_f32_e32 v147, v75
	v_exp_f32_e32 v148, v76
	v_exp_f32_e32 v149, v77
	ds_read_b128 v[70:73], v142 offset:27648
	ds_read_b128 v[74:77], v142 offset:27680
	s_nop 5
	v_exp_f32_e32 v82, v82
	s_waitcnt lgkmcnt(1)
	v_mfma_f32_32x32x16_bf16 v[34:49], v[70:73], v[66:69], v[34:49]
	ds_read_b128 v[70:73], v142 offset:32256
	v_exp_f32_e32 v83, v83
	v_exp_f32_e32 v84, v84
	v_exp_f32_e32 v85, v85
	v_exp_f32_e32 v86, v86
	v_exp_f32_e32 v87, v87
	v_exp_f32_e32 v88, v88
	s_waitcnt lgkmcnt(0)
	v_mfma_f32_32x32x16_bf16 v[18:33], v[70:73], v[66:69], v[18:33]
	ds_read_b128 v[70:73], v142 offset:32288
	v_exp_f32_e32 v89, v89
	v_exp_f32_e32 v90, v90
	v_exp_f32_e32 v91, v91
	v_exp_f32_e32 v92, v92
	v_exp_f32_e32 v93, v93
	v_exp_f32_e32 v94, v94
	v_mfma_f32_32x32x16_bf16 v[50:65], v[130:133], v[66:69], v[50:65]
	v_cvt_pk_bf16_f32 v66, v146, v147
	v_cvt_pk_bf16_f32 v67, v148, v149
	v_cvt_pk_bf16_f32 v68, v78, v79
	v_cvt_pk_bf16_f32 v69, v80, v81
	v_exp_f32_e32 v95, v95
	v_exp_f32_e32 v96, v96
	v_exp_f32_e32 v97, v97
	s_waitcnt lgkmcnt(0)
	v_mfma_f32_32x32x16_bf16 v[18:33], v[70:73], v[66:69], v[18:33]
	ds_read_b128 v[70:73], v142 offset:27712
	v_mfma_f32_32x32x16_bf16 v[34:49], v[74:77], v[66:69], v[34:49]
	v_mfma_f32_32x32x16_bf16 v[50:65], v[130:133], v[66:69], v[50:65]
	v_cvt_pk_bf16_f32 v66, v82, v83
	v_cvt_pk_bf16_f32 v67, v84, v85
	v_cvt_pk_bf16_f32 v68, v86, v87
	v_cvt_pk_bf16_f32 v69, v88, v89
	s_waitcnt lgkmcnt(0)
	s_nop 0
	v_mfma_f32_32x32x16_bf16 v[34:49], v[70:73], v[66:69], v[34:49]
	ds_read_b128 v[70:73], v142 offset:32320
	s_waitcnt lgkmcnt(0)
	v_mfma_f32_32x32x16_bf16 v[18:33], v[70:73], v[66:69], v[18:33]
	ds_read_b128 v[70:73], v142 offset:27744
	v_mfma_f32_32x32x16_bf16 v[50:65], v[130:133], v[66:69], v[50:65]
	v_cvt_pk_bf16_f32 v66, v90, v91
	v_cvt_pk_bf16_f32 v67, v92, v93
	v_cvt_pk_bf16_f32 v68, v94, v95
	v_cvt_pk_bf16_f32 v69, v96, v97
	s_waitcnt lgkmcnt(0)
	s_nop 0
	v_mfma_f32_32x32x16_bf16 v[34:49], v[70:73], v[66:69], v[34:49]
	ds_read_b128 v[70:73], v142 offset:32352
	s_waitcnt lgkmcnt(0)
	s_barrier
	v_mfma_f32_32x32x16_bf16 v[50:65], v[130:133], v[66:69], v[50:65]
	v_mfma_f32_32x32x16_bf16 v[18:33], v[70:73], v[66:69], v[18:33]
	s_nop 11
	v_mov_b32_e32 v51, 0
	v_mov_b32_e32 v52, 0
	v_lshl_add_u64 v[132:133], v[136:137], 0, v[0:1]
	v_lshl_add_u64 v[130:131], v[138:139], 0, v[0:1]
	s_nop 0
	v_readfirstlane_b32 s92, v132
	v_readfirstlane_b32 s93, v133
	v_readfirstlane_b32 s94, v130
	v_readfirstlane_b32 s95, v131
	s_nop 3
	v_subrev_u32_e32 v53, s92, v132
	v_subrev_u32_e32 v54, s94, v130
	s_add_u32 s92, s92, 0x2000
	s_addc_u32 s93, s93, 0
	s_branch .LBB0_261
	.p2align	8

; #define PG8_STAGE(bufoff, gbase, voff) do { _Pragma("unroll") for (int _i = 0; _i < 2; ++_i) \
;     __builtin_amdgcn_global_load_lds((const unsigned*)((const char*)(gbase) + (voff)[_i]), (LAS unsigned*)(lds + (bufoff) + ldsw + _i * 8192), 16, 0, 0); } while (0)
; #define PG8_WAIT_V(n) asm volatile("s_waitcnt vmcnt(" #n ")" ::: "memory")
; #define PG8_BAR __builtin_amdgcn_s_barrier()
; template <class Epi, class Sched>
; DI void gemm_phase(LAS unsigned char* lds, const Gemm g, const Sched& S, const Epi& E) {
;     ...
;   f32x4 acc[2][2][4][2];
; #pragma unroll
;   for (int a = 0; a < 2; ++a)
; #pragma unroll
;     for (int b = 0; b < 2; ++b)
; #pragma unroll
;       for (int m = 0; m < 4; ++m)
; #pragma unroll
;         for (int n = 0; n < 2; ++n) acc[a][b][m][n] = (f32x4){0.f, 0.f, 0.f, 0.f};
;   bf16x8 At[4][2], B0[2][2], B1[2][2];
;   const char* cA = (const char*)g.A + (size_t)cur.pm * tstep; const char* cB = (const char*)g.Bt + (size_t)cur.pn * tstep;
;   PG8_STAGE(PG8_SB(0, 0), cB, voffB); PG8_STAGE(PG8_SA(0, 0), cA, voffA); PG8_STAGE(PG8_SB(0, 1), cB + hstepB, voffB); PG8_STAGE(PG8_SA(0, 1), cA + hstep, voffA);
;   if (wr == 1) PG8_BAR;
;   PG8_WAIT_V(4); PG8_BAR;
;   PG8_STAGE(PG8_SB(1, 0), cB + kstep, voffB); PG8_STAGE(PG8_SA(1, 0), cA + kstep, voffA); PG8_STAGE(PG8_SB(1, 1), cB + hstepB + kstep, voffB);
;   PG8_WAIT_V(6); PG8_BAR;
.LBB0_489:
	v_lshl_add_u64 v[4:5], s[2:3], 0, v[0:1]
	v_mov_b32_e32 v127, v1
	v_lshl_add_u64 v[6:7], s[2:3], 0, v[126:127]
	v_and_b32_e32 v128, 15, v2
	v_bfe_u32 v132, v2, 4, 2
	s_add_i32 m0, s18, 0x18000
	v_lshl_add_u64 v[2:3], v[4:5], 0, s[70:71]
	v_lshl_add_u64 v[8:9], s[4:5], 0, v[0:1]
	s_waitcnt vmcnt(4)
	s_barrier
	global_load_lds_dwordx4 v[2:3], off
	v_lshl_add_u64 v[2:3], v[6:7], 0, s[70:71]
	s_add_i32 m0, s18, 0x1a000
	s_add_i32 s22, s18, 0x8000
	v_lshl_add_u64 v[10:11], s[4:5], 0, v[126:127]
	global_load_lds_dwordx4 v[2:3], off
	v_lshl_add_u64 v[2:3], v[8:9], 0, s[70:71]
	s_mov_b32 m0, s22
	s_add_i32 s23, s18, 0xa000
	v_lshl_add_u64 v[12:13], s[8:9], 0, v[0:1]
	global_load_lds_dwordx4 v[2:3], off
	v_lshl_add_u64 v[2:3], v[10:11], 0, s[70:71]
	s_mov_b32 m0, s23
	v_lshl_add_u64 v[14:15], s[8:9], 0, v[126:127]
	global_load_lds_dwordx4 v[2:3], off
	s_add_i32 m0, s18, 0x1c000
	v_lshl_add_u64 v[2:3], v[12:13], 0, s[70:71]
	global_load_lds_dwordx4 v[2:3], off
	v_lshl_add_u64 v[2:3], v[14:15], 0, s[70:71]
	s_add_i32 m0, s18, 0x1e000
	s_lshl_b32 s8, s11, 5
	global_load_lds_dwordx4 v[2:3], off
	s_waitcnt vmcnt(6)
	s_and_b32 s16, s8, 0x60
	v_mov_b32_e32 v137, 0
	v_lshl_or_b32 v146, s10, 6, v128
	s_cmp_lt_i32 s6, 64
	v_mov_b32_e32 v136, v137
	v_mov_b32_e32 v135, v137
	v_mov_b32_e32 v134, v137
	v_mov_b32_e32 v125, v137
	v_mov_b32_e32 v124, v137
	v_mov_b32_e32 v123, v137
	v_mov_b32_e32 v122, v137
	v_mov_b32_e32 v113, v137
	v_mov_b32_e32 v112, v137
	v_mov_b32_e32 v111, v137
	v_mov_b32_e32 v110, v137
	v_mov_b32_e32 v109, v137
	v_mov_b32_e32 v108, v137
	v_mov_b32_e32 v107, v137
	v_mov_b32_e32 v106, v137
	v_mov_b32_e32 v97, v137
	v_mov_b32_e32 v96, v137
	v_mov_b32_e32 v95, v137
	v_mov_b32_e32 v94, v137
	v_mov_b32_e32 v93, v137
	v_mov_b32_e32 v92, v137
	v_mov_b32_e32 v91, v137
	v_mov_b32_e32 v90, v137
	v_mov_b32_e32 v81, v137
	v_mov_b32_e32 v80, v137
	v_mov_b32_e32 v79, v137
	v_mov_b32_e32 v78, v137
	v_mov_b32_e32 v77, v137
	v_mov_b32_e32 v76, v137
	v_mov_b32_e32 v75, v137
	v_mov_b32_e32 v74, v137
	v_mov_b32_e32 v121, v137
	v_mov_b32_e32 v120, v137
	v_mov_b32_e32 v119, v137
	v_mov_b32_e32 v118, v137
	v_mov_b32_e32 v117, v137
	v_mov_b32_e32 v116, v137
	v_mov_b32_e32 v115, v137
	v_mov_b32_e32 v114, v137
	v_mov_b32_e32 v105, v137
	v_mov_b32_e32 v104, v137
	v_mov_b32_e32 v103, v137
	v_mov_b32_e32 v102, v137
	v_mov_b32_e32 v101, v137
	v_mov_b32_e32 v100, v137
	v_mov_b32_e32 v99, v137
	v_mov_b32_e32 v98, v137
	v_mov_b32_e32 v89, v137
	v_mov_b32_e32 v88, v137
	v_mov_b32_e32 v87, v137
	v_mov_b32_e32 v86, v137
	v_mov_b32_e32 v85, v137
	v_mov_b32_e32 v84, v137
	v_mov_b32_e32 v83, v137
	v_mov_b32_e32 v82, v137
	v_mov_b32_e32 v73, v137
	v_mov_b32_e32 v72, v137
	v_mov_b32_e32 v71, v137
	v_mov_b32_e32 v70, v137
	v_mov_b32_e32 v69, v137
	v_mov_b32_e32 v68, v137
	v_mov_b32_e32 v67, v137
	v_mov_b32_e32 v66, v137
	v_mov_b32_e32 v65, v137
	v_mov_b32_e32 v64, v137
	v_mov_b32_e32 v63, v137
	v_mov_b32_e32 v62, v137
	v_mov_b32_e32 v61, v137
	v_mov_b32_e32 v60, v137
	v_mov_b32_e32 v59, v137
	v_mov_b32_e32 v58, v137
	v_mov_b32_e32 v53, v137
	v_mov_b32_e32 v52, v137
	v_mov_b32_e32 v51, v137
	v_mov_b32_e32 v50, v137
	v_mov_b32_e32 v45, v137
	v_mov_b32_e32 v44, v137
	v_mov_b32_e32 v43, v137
	v_mov_b32_e32 v42, v137
	v_mov_b32_e32 v37, v137
	v_mov_b32_e32 v36, v137
	v_mov_b32_e32 v35, v137
	v_mov_b32_e32 v34, v137
	v_mov_b32_e32 v29, v137
	v_mov_b32_e32 v28, v137
	v_mov_b32_e32 v27, v137
	v_mov_b32_e32 v26, v137
	v_mov_b32_e32 v21, v137
	v_mov_b32_e32 v20, v137
	v_mov_b32_e32 v19, v137
	v_mov_b32_e32 v18, v137
	v_mov_b32_e32 v13, v137
	v_mov_b32_e32 v12, v137
	v_mov_b32_e32 v11, v137
	v_mov_b32_e32 v10, v137
	v_mov_b32_e32 v57, v137
	v_mov_b32_e32 v56, v137
	v_mov_b32_e32 v55, v137
	v_mov_b32_e32 v54, v137
	v_mov_b32_e32 v49, v137
	v_mov_b32_e32 v48, v137
	v_mov_b32_e32 v47, v137
	v_mov_b32_e32 v46, v137
	v_mov_b32_e32 v41, v137
	v_mov_b32_e32 v40, v137
	v_mov_b32_e32 v39, v137
	v_mov_b32_e32 v38, v137
	v_mov_b32_e32 v33, v137
	v_mov_b32_e32 v32, v137
	v_mov_b32_e32 v31, v137
	v_mov_b32_e32 v30, v137
	v_mov_b32_e32 v25, v137
	v_mov_b32_e32 v24, v137
	v_mov_b32_e32 v23, v137
	v_mov_b32_e32 v22, v137
	v_mov_b32_e32 v17, v137
	v_mov_b32_e32 v16, v137
	v_mov_b32_e32 v15, v137
	v_mov_b32_e32 v14, v137
	v_mov_b32_e32 v9, v137
	v_mov_b32_e32 v8, v137
	v_mov_b32_e32 v7, v137
	v_mov_b32_e32 v6, v137
	v_mov_b32_e32 v5, v137
	v_mov_b32_e32 v4, v137
	v_mov_b32_e32 v3, v137
	v_mov_b32_e32 v2, v137
	s_barrier
; template <class Epi, class Sched>
; DI void gemm_phase(LAS unsigned char* lds, const Gemm g, const Sched& S, const Epi& E) {
;     ...
;   const int nt = K / BK;
;   unsigned voffA[2], voffB[2];
; #pragma unroll
;   for (int i = 0; i < 2; ++i) {
;     int R, C; stage_rc(tid * 16 + i * 8192, R, C);
;     int Rb = R;
;     if (Epi::BMAP == 1) Rb = (R & ~31) + perm32(R & 31);
;     if (Epi::BMAP == 2) Rb = 64 * (R >> 5) + perm32(R & 31);
;     voffA[i] = (unsigned)(R * K + C) * 2u; voffB[i] = (unsigned)(Rb * K + C) * 2u;
;   }
;   const size_t kstep = (size_t)(BK * 2);
;   const size_t hstep = (size_t)HALF * K * 2;
;   const size_t hstepB = (Epi::BMAP == 2) ? (size_t)32 * K * 2 : hstep;
;   const size_t tstep = 2 * hstep;
;   const unsigned ldsw = (unsigned)wid * 1024u;
;   const int aoff = lds_byte(wr * 64 + fr, fq * 8), boff = lds_byte(wc * 32 + fr, fq * 8);
;     ...
; #pragma unroll
;   for (int a = 0; a < 2; ++a)
; #pragma unroll
;     for (int b = 0; b < 2; ++b)
; #pragma unroll
;       for (int m = 0; m < 4; ++m)
; #pragma unroll
;         for (int n = 0; n < 2; ++n) acc[a][b][m][n] = (f32x4){0.f, 0.f, 0.f, 0.f};
	s_cbranch_scc1 .LBB0_493
	s_lshr_b32 s7, s7, 26
	s_add_i32 s7, s6, s7
	s_ashr_i32 s24, s7, 6
	v_lshlrev_b32_e32 v2, 4, v132
	v_lshlrev_b32_e32 v3, 6, v146
	s_movk_i32 s7, 0x3c0
	v_lshlrev_b32_e32 v4, 2, v146
	v_and_or_b32 v3, v3, s7, v2
	s_lshl_b32 s7, s10, 13
	v_and_b32_e32 v4, 32, v4
	v_bitop3_b32 v3, v3, s7, v4 bitop3:0xde
	v_lshlrev_b32_e32 v4, 2, v128
	v_lshl_or_b32 v2, v128, 6, v2
	s_lshl_b32 s7, s16, 7
	v_and_b32_e32 v4, 32, v4
	v_bitop3_b32 v133, v2, s7, v4 bitop3:0xde
	s_lshl_b32 s7, s13, 9
	s_bitset1_b32 s7, 8
	s_add_i32 s25, s24, -2
	s_mul_hi_i32 s8, s7, s6
	s_mul_i32 s7, s7, s6
	s_add_u32 s6, s90, s7
	s_addc_u32 s7, s91, s8
	v_mov_b32_e32 v2, 0
	v_lshl_add_u64 v[128:129], s[6:7], 0, v[0:1]
	v_lshl_add_u64 v[130:131], s[6:7], 0, v[126:127]
	s_mov_b32 s8, 0
	s_mov_b64 s[6:7], 0x2000080
	v_add_u32_e32 v138, 16, v3
	v_mov_b32_e32 v3, v2
	v_mov_b32_e32 v4, v2
	v_mov_b32_e32 v5, v2
	v_mov_b32_e32 v6, v2
	v_mov_b32_e32 v7, v2
	v_mov_b32_e32 v8, v2
	v_mov_b32_e32 v9, v2
	v_mov_b32_e32 v14, v2
	v_mov_b32_e32 v15, v2
	v_mov_b32_e32 v16, v2
	v_mov_b32_e32 v17, v2
	v_mov_b32_e32 v22, v2
	v_mov_b32_e32 v23, v2
	v_mov_b32_e32 v24, v2
	v_mov_b32_e32 v25, v2
	v_mov_b32_e32 v30, v2
	v_mov_b32_e32 v31, v2
	v_mov_b32_e32 v32, v2
	v_mov_b32_e32 v33, v2
	v_mov_b32_e32 v38, v2
	v_mov_b32_e32 v39, v2
	v_mov_b32_e32 v40, v2
	v_mov_b32_e32 v41, v2
	v_mov_b32_e32 v46, v2
	v_mov_b32_e32 v47, v2
	v_mov_b32_e32 v48, v2
	v_mov_b32_e32 v49, v2
	v_mov_b32_e32 v54, v2
	v_mov_b32_e32 v55, v2
	v_mov_b32_e32 v56, v2
	v_mov_b32_e32 v57, v2
	v_mov_b32_e32 v10, v2
	v_mov_b32_e32 v11, v2
	v_mov_b32_e32 v12, v2
	v_mov_b32_e32 v13, v2
	v_mov_b32_e32 v18, v2
	v_mov_b32_e32 v19, v2
	v_mov_b32_e32 v20, v2
	v_mov_b32_e32 v21, v2
	v_mov_b32_e32 v26, v2
	v_mov_b32_e32 v27, v2
	v_mov_b32_e32 v28, v2
	v_mov_b32_e32 v29, v2
	v_mov_b32_e32 v34, v2
	v_mov_b32_e32 v35, v2
	v_mov_b32_e32 v36, v2
	v_mov_b32_e32 v37, v2
	v_mov_b32_e32 v42, v2
	v_mov_b32_e32 v43, v2
	v_mov_b32_e32 v44, v2
	v_mov_b32_e32 v45, v2
	v_mov_b32_e32 v50, v2
	v_mov_b32_e32 v51, v2
	v_mov_b32_e32 v52, v2
	v_mov_b32_e32 v53, v2
	v_mov_b32_e32 v58, v2
	v_mov_b32_e32 v59, v2
	v_mov_b32_e32 v60, v2
	v_mov_b32_e32 v61, v2
	v_mov_b32_e32 v62, v2
	v_mov_b32_e32 v63, v2
	v_mov_b32_e32 v64, v2
	v_mov_b32_e32 v65, v2
	v_mov_b32_e32 v66, v2
	v_mov_b32_e32 v67, v2
	v_mov_b32_e32 v68, v2
	v_mov_b32_e32 v69, v2
	v_mov_b32_e32 v70, v2
	v_mov_b32_e32 v71, v2
	v_mov_b32_e32 v72, v2
	v_mov_b32_e32 v73, v2
	v_mov_b32_e32 v82, v2
	v_mov_b32_e32 v83, v2
	v_mov_b32_e32 v84, v2
	v_mov_b32_e32 v85, v2
	v_mov_b32_e32 v86, v2
	v_mov_b32_e32 v87, v2
	v_mov_b32_e32 v88, v2
	v_mov_b32_e32 v89, v2
	v_mov_b32_e32 v98, v2
	v_mov_b32_e32 v99, v2
	v_mov_b32_e32 v100, v2
	v_mov_b32_e32 v101, v2
	v_mov_b32_e32 v102, v2
	v_mov_b32_e32 v103, v2
	v_mov_b32_e32 v104, v2
	v_mov_b32_e32 v105, v2
	v_mov_b32_e32 v114, v2
	v_mov_b32_e32 v115, v2
	v_mov_b32_e32 v116, v2
	v_mov_b32_e32 v117, v2
	v_mov_b32_e32 v118, v2
	v_mov_b32_e32 v119, v2
	v_mov_b32_e32 v120, v2
	v_mov_b32_e32 v121, v2
	v_mov_b32_e32 v74, v2
	v_mov_b32_e32 v75, v2
	v_mov_b32_e32 v76, v2
	v_mov_b32_e32 v77, v2
	v_mov_b32_e32 v78, v2
	v_mov_b32_e32 v79, v2
	v_mov_b32_e32 v80, v2
	v_mov_b32_e32 v81, v2
	v_mov_b32_e32 v90, v2
	v_mov_b32_e32 v91, v2
	v_mov_b32_e32 v92, v2
	v_mov_b32_e32 v93, v2
	v_mov_b32_e32 v94, v2
	v_mov_b32_e32 v95, v2
	v_mov_b32_e32 v96, v2
	v_mov_b32_e32 v97, v2
	v_mov_b32_e32 v106, v2
	v_mov_b32_e32 v107, v2
	v_mov_b32_e32 v108, v2
	v_mov_b32_e32 v109, v2
	v_mov_b32_e32 v110, v2
	v_mov_b32_e32 v111, v2
	v_mov_b32_e32 v112, v2
	v_mov_b32_e32 v113, v2
	v_mov_b32_e32 v122, v2
	v_mov_b32_e32 v123, v2
	v_mov_b32_e32 v124, v2
	v_mov_b32_e32 v125, v2
	v_mov_b32_e32 v134, v2
	v_mov_b32_e32 v135, v2
	v_mov_b32_e32 v136, v2
	v_mov_b32_e32 v137, v2
	s_waitcnt vmcnt(0)
	.p2align	8

; template <class Epi, class Sched>
; DI void gemm_phase(LAS unsigned char* lds, const Gemm g, const Sched& S, const Epi& E) {
;     ...
;     if (!has_next) break;
; #pragma unroll
;     for (int a = 0; a < 2; ++a)
; #pragma unroll
;       for (int b = 0; b < 2; ++b)
; #pragma unroll
;         for (int m = 0; m < 4; ++m)
; #pragma unroll
;           for (int n = 0; n < 2; ++n) acc[a][b][m][n] = (f32x4){0.f, 0.f, 0.f, 0.f};
;     cur = nxt; cA = nA; cB = nB; ++ui;
;   DI void operator()(const f32x4 (&acc)[2][2][4][2], const Unit& u, int wr, int wc, int fr, int fq) const {
;     ...
;     int gi = 0;
;     if (chunk < 6) gi = 0; else if (chunk < 8) gi = 1; else if (chunk < 14) gi = 2; else if (chunk < 18) gi = 3;
;     else if (chunk < 28) gi = 4; else gi = 5;
;     const bool ropeT = (gi == 0 || gi == 1 || gi == 4 || gi == 5) && rowbase == 0;
;     const float* gam = qkn + gi * 64;
;     const float qs = (gi == 0 || gi == 2 || gi == 4) ? 0.125f * LOG2E : 1.f;
.LBB0_517:
	v_mov_b32_e32 v177, 0
	s_andn2_b64 vcc, exec, s[18:19]
	v_mov_b32_e32 v176, v177
	v_mov_b32_e32 v175, v177
	v_mov_b32_e32 v174, v177
	v_mov_b32_e32 v173, v177
	v_mov_b32_e32 v172, v177
	v_mov_b32_e32 v171, v177
	v_mov_b32_e32 v170, v177
	s_waitcnt vmcnt(0)
	v_mov_b32_e32 v161, v177
	v_mov_b32_e32 v160, v177
	v_mov_b32_e32 v159, v177
	v_mov_b32_e32 v158, v177
	v_mov_b32_e32 v157, v177
	v_mov_b32_e32 v156, v177
	v_mov_b32_e32 v155, v177
	v_mov_b32_e32 v154, v177
	v_mov_b32_e32 v145, v177
	v_mov_b32_e32 v144, v177
	v_mov_b32_e32 v143, v177
	v_mov_b32_e32 v142, v177
	v_mov_b32_e32 v141, v177
	v_mov_b32_e32 v140, v177
	v_mov_b32_e32 v139, v177
	v_mov_b32_e32 v138, v177
	v_mov_b32_e32 v113, v177
	v_mov_b32_e32 v112, v177
	v_mov_b32_e32 v111, v177
	v_mov_b32_e32 v110, v177
	v_mov_b32_e32 v109, v177
	v_mov_b32_e32 v108, v177
	v_mov_b32_e32 v107, v177
	v_mov_b32_e32 v106, v177
	v_mov_b32_e32 v169, v177
	v_mov_b32_e32 v168, v177
	v_mov_b32_e32 v167, v177
	v_mov_b32_e32 v166, v177
	v_mov_b32_e32 v165, v177
	v_mov_b32_e32 v164, v177
	v_mov_b32_e32 v163, v177
	v_mov_b32_e32 v162, v177
	v_mov_b32_e32 v153, v177
	v_mov_b32_e32 v152, v177
	v_mov_b32_e32 v151, v177
	v_mov_b32_e32 v150, v177
	v_mov_b32_e32 v149, v177
	v_mov_b32_e32 v148, v177
	v_mov_b32_e32 v147, v177
	v_mov_b32_e32 v146, v177
	v_mov_b32_e32 v137, v177
	v_mov_b32_e32 v136, v177
	v_mov_b32_e32 v135, v177
	v_mov_b32_e32 v134, v177
	v_mov_b32_e32 v133, v177
	v_mov_b32_e32 v132, v177
	v_mov_b32_e32 v131, v177
	v_mov_b32_e32 v130, v177
	v_mov_b32_e32 v105, v177
	v_mov_b32_e32 v104, v177
	v_mov_b32_e32 v103, v177
	v_mov_b32_e32 v102, v177
	v_mov_b32_e32 v93, v177
	v_mov_b32_e32 v92, v177
	v_mov_b32_e32 v91, v177
	v_mov_b32_e32 v90, v177
	v_mov_b32_e32 v65, v177
	v_mov_b32_e32 v64, v177
	v_mov_b32_e32 v63, v177
	v_mov_b32_e32 v62, v177
	v_mov_b32_e32 v61, v177
	v_mov_b32_e32 v60, v177
	v_mov_b32_e32 v59, v177
	v_mov_b32_e32 v58, v177
	v_mov_b32_e32 v49, v177
	v_mov_b32_e32 v48, v177
	v_mov_b32_e32 v47, v177
	v_mov_b32_e32 v46, v177
	v_mov_b32_e32 v45, v177
	v_mov_b32_e32 v44, v177
	v_mov_b32_e32 v43, v177
	v_mov_b32_e32 v42, v177
	v_mov_b32_e32 v33, v177
	v_mov_b32_e32 v32, v177
	v_mov_b32_e32 v31, v177
	v_mov_b32_e32 v30, v177
	v_mov_b32_e32 v29, v177
	v_mov_b32_e32 v28, v177
	v_mov_b32_e32 v27, v177
	v_mov_b32_e32 v26, v177
	v_mov_b32_e32 v17, v177
	v_mov_b32_e32 v16, v177
	v_mov_b32_e32 v15, v177
	v_mov_b32_e32 v14, v177
	v_mov_b32_e32 v13, v177
	v_mov_b32_e32 v12, v177
	v_mov_b32_e32 v11, v177
	v_mov_b32_e32 v10, v177
	v_mov_b32_e32 v57, v177
	v_mov_b32_e32 v56, v177
	v_mov_b32_e32 v55, v177
	v_mov_b32_e32 v54, v177
	v_mov_b32_e32 v53, v177
	v_mov_b32_e32 v52, v177
	v_mov_b32_e32 v51, v177
	v_mov_b32_e32 v50, v177
	v_mov_b32_e32 v41, v177
	v_mov_b32_e32 v40, v177
	v_mov_b32_e32 v39, v177
	v_mov_b32_e32 v38, v177
	v_mov_b32_e32 v37, v177
	v_mov_b32_e32 v36, v177
	v_mov_b32_e32 v35, v177
	v_mov_b32_e32 v34, v177
	v_mov_b32_e32 v25, v177
	v_mov_b32_e32 v24, v177
	v_mov_b32_e32 v23, v177
	v_mov_b32_e32 v22, v177
	v_mov_b32_e32 v21, v177
	v_mov_b32_e32 v20, v177
	v_mov_b32_e32 v19, v177
	v_mov_b32_e32 v18, v177
	v_mov_b32_e32 v9, v177
	v_mov_b32_e32 v8, v177
	v_mov_b32_e32 v7, v177
	v_mov_b32_e32 v6, v177
	v_mov_b32_e32 v5, v177
	v_mov_b32_e32 v4, v177
	v_mov_b32_e32 v3, v177
	v_mov_b32_e32 v2, v177
	s_cbranch_vccnz .LBB0_521
	s_add_u32 s2, s2, 0x80
	s_addc_u32 s3, s3, 0
	s_add_u32 s11, s8, 0x100
	v_mov_b32_e32 v2, 0
	v_mov_b32_e32 v200, v184
	v_mov_b32_e32 v201, 0x358637bd
	v_mov_b32_e32 v210, 0x3e38aa3b
	v_mov_b32_e32 v217, 1
	v_mov_b64_e32 v[178:179], 0x200
	s_addc_u32 s22, s9, 0
	s_mov_b32 s6, 0
	v_mov_b32_e32 v3, v2
	v_mov_b32_e32 v4, v2
	v_mov_b32_e32 v5, v2
	v_mov_b32_e32 v6, v2
	v_mov_b32_e32 v7, v2
	v_mov_b32_e32 v8, v2
	v_mov_b32_e32 v9, v2
	v_mov_b32_e32 v18, v2
	v_mov_b32_e32 v19, v2
	v_mov_b32_e32 v20, v2
	v_mov_b32_e32 v21, v2
	v_mov_b32_e32 v22, v2
	v_mov_b32_e32 v23, v2
	v_mov_b32_e32 v24, v2
	v_mov_b32_e32 v25, v2
	v_mov_b32_e32 v34, v2
	v_mov_b32_e32 v35, v2
	v_mov_b32_e32 v36, v2
	v_mov_b32_e32 v37, v2
	v_mov_b32_e32 v38, v2
	v_mov_b32_e32 v39, v2
	v_mov_b32_e32 v40, v2
	v_mov_b32_e32 v41, v2
	v_mov_b32_e32 v50, v2
	v_mov_b32_e32 v51, v2
	v_mov_b32_e32 v52, v2
	v_mov_b32_e32 v53, v2
	v_mov_b32_e32 v54, v2
	v_mov_b32_e32 v55, v2
	v_mov_b32_e32 v56, v2
	v_mov_b32_e32 v57, v2
	v_mov_b32_e32 v10, v2
	v_mov_b32_e32 v11, v2
	v_mov_b32_e32 v12, v2
	v_mov_b32_e32 v13, v2
	v_mov_b32_e32 v14, v2
	v_mov_b32_e32 v15, v2
	v_mov_b32_e32 v16, v2
	v_mov_b32_e32 v17, v2
	v_mov_b32_e32 v26, v2
	v_mov_b32_e32 v27, v2
	v_mov_b32_e32 v28, v2
	v_mov_b32_e32 v29, v2
	v_mov_b32_e32 v30, v2
	v_mov_b32_e32 v31, v2
	v_mov_b32_e32 v32, v2
	v_mov_b32_e32 v33, v2
	v_mov_b32_e32 v42, v2
	v_mov_b32_e32 v43, v2
	v_mov_b32_e32 v44, v2
	v_mov_b32_e32 v45, v2
	v_mov_b32_e32 v46, v2
	v_mov_b32_e32 v47, v2
	v_mov_b32_e32 v48, v2
	v_mov_b32_e32 v49, v2
	v_mov_b32_e32 v58, v2
	v_mov_b32_e32 v59, v2
	v_mov_b32_e32 v60, v2
	v_mov_b32_e32 v61, v2
	v_mov_b32_e32 v62, v2
	v_mov_b32_e32 v63, v2
	v_mov_b32_e32 v64, v2
	v_mov_b32_e32 v65, v2
	v_mov_b32_e32 v90, v2
	v_mov_b32_e32 v91, v2
	v_mov_b32_e32 v92, v2
	v_mov_b32_e32 v93, v2
	v_mov_b32_e32 v102, v2
	v_mov_b32_e32 v103, v2
	v_mov_b32_e32 v104, v2
	v_mov_b32_e32 v105, v2
	v_mov_b32_e32 v130, v2
	v_mov_b32_e32 v131, v2
	v_mov_b32_e32 v132, v2
	v_mov_b32_e32 v133, v2
	v_mov_b32_e32 v134, v2
	v_mov_b32_e32 v135, v2
	v_mov_b32_e32 v136, v2
	v_mov_b32_e32 v137, v2
	v_mov_b32_e32 v146, v2
	v_mov_b32_e32 v147, v2
	v_mov_b32_e32 v148, v2
	v_mov_b32_e32 v149, v2
	v_mov_b32_e32 v150, v2
	v_mov_b32_e32 v151, v2
	v_mov_b32_e32 v152, v2
	v_mov_b32_e32 v153, v2
	v_mov_b32_e32 v162, v2
	v_mov_b32_e32 v163, v2
	v_mov_b32_e32 v164, v2
	v_mov_b32_e32 v165, v2
	v_mov_b32_e32 v166, v2
	v_mov_b32_e32 v167, v2
	v_mov_b32_e32 v168, v2
	v_mov_b32_e32 v169, v2
	v_mov_b32_e32 v106, v2
	v_mov_b32_e32 v107, v2
	v_mov_b32_e32 v108, v2
	v_mov_b32_e32 v109, v2
	v_mov_b32_e32 v110, v2
	v_mov_b32_e32 v111, v2
	v_mov_b32_e32 v112, v2
	v_mov_b32_e32 v113, v2
	v_mov_b32_e32 v138, v2
	v_mov_b32_e32 v139, v2
	v_mov_b32_e32 v140, v2
	v_mov_b32_e32 v141, v2
	v_mov_b32_e32 v142, v2
	v_mov_b32_e32 v143, v2
	v_mov_b32_e32 v144, v2
	v_mov_b32_e32 v145, v2
	v_mov_b32_e32 v154, v2
	v_mov_b32_e32 v155, v2
	v_mov_b32_e32 v156, v2
	v_mov_b32_e32 v157, v2
	v_mov_b32_e32 v158, v2
	v_mov_b32_e32 v159, v2
	v_mov_b32_e32 v160, v2
	v_mov_b32_e32 v161, v2
	v_mov_b32_e32 v170, v2
	v_mov_b32_e32 v171, v2
	v_mov_b32_e32 v172, v2
	v_mov_b32_e32 v173, v2
	v_mov_b32_e32 v174, v2
	v_mov_b32_e32 v175, v2
	v_mov_b32_e32 v176, v2
	v_mov_b32_e32 v177, v2
	.p2align	8

; #define PG8_STAGE(bufoff, gbase, voff) do { _Pragma("unroll") for (int _i = 0; _i < 2; ++_i) \
;     __builtin_amdgcn_global_load_lds((const unsigned*)((const char*)(gbase) + (voff)[_i]), (LAS unsigned*)(lds + (bufoff) + ldsw + _i * 8192), 16, 0, 0); } while (0)
; #define PG8_WAIT_V(n) asm volatile("s_waitcnt vmcnt(" #n ")" ::: "memory")
; #define PG8_BAR __builtin_amdgcn_s_barrier()
; template <class Epi, class Sched>
; DI void gemm_phase(LAS unsigned char* lds, const Gemm g, const Sched& S, const Epi& E) {
;     ...
;   f32x4 acc[2][2][4][2];
; #pragma unroll
;   for (int a = 0; a < 2; ++a)
; #pragma unroll
;     for (int b = 0; b < 2; ++b)
; #pragma unroll
;       for (int m = 0; m < 4; ++m)
; #pragma unroll
;         for (int n = 0; n < 2; ++n) acc[a][b][m][n] = (f32x4){0.f, 0.f, 0.f, 0.f};
;   bf16x8 At[4][2], B0[2][2], B1[2][2];
;   const char* cA = (const char*)g.A + (size_t)cur.pm * tstep; const char* cB = (const char*)g.Bt + (size_t)cur.pn * tstep;
;   PG8_STAGE(PG8_SB(0, 0), cB, voffB); PG8_STAGE(PG8_SA(0, 0), cA, voffA); PG8_STAGE(PG8_SB(0, 1), cB + hstepB, voffB); PG8_STAGE(PG8_SA(0, 1), cA + hstep, voffA);
;   if (wr == 1) PG8_BAR;
;   PG8_WAIT_V(4); PG8_BAR;
;   PG8_STAGE(PG8_SB(1, 0), cB + kstep, voffB); PG8_STAGE(PG8_SA(1, 0), cA + kstep, voffA); PG8_STAGE(PG8_SB(1, 1), cB + hstepB + kstep, voffB);
;   PG8_WAIT_V(6); PG8_BAR;
.LBB0_829:
	v_lshl_add_u64 v[4:5], s[4:5], 0, v[0:1]
	v_mov_b32_e32 v83, v1
	v_lshl_add_u64 v[6:7], s[4:5], 0, v[82:83]
	v_mov_b32_e32 v87, v1
	v_and_b32_e32 v150, 15, v2
	v_bfe_u32 v148, v2, 4, 2
	s_add_i32 m0, s18, 0x18000
	v_lshl_add_u64 v[2:3], v[4:5], 0, s[70:71]
	v_lshl_add_u64 v[8:9], s[6:7], 0, v[86:87]
	v_mov_b32_e32 v85, v1
	s_waitcnt vmcnt(4)
	s_barrier
	global_load_lds_dwordx4 v[2:3], off
	v_lshl_add_u64 v[2:3], v[6:7], 0, s[70:71]
	s_add_i32 m0, s18, 0x1a000
	s_add_i32 s22, s18, 0x8000
	v_lshl_add_u64 v[10:11], s[6:7], 0, v[84:85]
	global_load_lds_dwordx4 v[2:3], off
	v_lshl_add_u64 v[2:3], v[8:9], 0, s[70:71]
	s_mov_b32 m0, s22
	s_add_i32 s23, s18, 0xa000
	v_lshl_add_u64 v[12:13], s[10:11], 0, v[0:1]
	global_load_lds_dwordx4 v[2:3], off
	v_lshl_add_u64 v[2:3], v[10:11], 0, s[70:71]
	s_mov_b32 m0, s23
	v_lshl_add_u64 v[14:15], s[10:11], 0, v[82:83]
	global_load_lds_dwordx4 v[2:3], off
	s_add_i32 m0, s18, 0x1c000
	v_lshl_add_u64 v[2:3], v[12:13], 0, s[70:71]
	global_load_lds_dwordx4 v[2:3], off
	v_lshl_add_u64 v[2:3], v[14:15], 0, s[70:71]
	s_add_i32 m0, s18, 0x1e000
	s_and_b32 s16, s13, 3
	global_load_lds_dwordx4 v[2:3], off
	s_waitcnt vmcnt(6)
	s_lshl_b32 s15, s12, 6
	v_mov_b32_e32 v145, 0
	s_cmp_lt_i32 s8, 64
	v_mov_b32_e32 v144, v145
	v_mov_b32_e32 v143, v145
	v_mov_b32_e32 v142, v145
	v_mov_b32_e32 v141, v145
	v_mov_b32_e32 v140, v145
	v_mov_b32_e32 v139, v145
	v_mov_b32_e32 v138, v145
	v_mov_b32_e32 v129, v145
	v_mov_b32_e32 v128, v145
	v_mov_b32_e32 v127, v145
	v_mov_b32_e32 v126, v145
	v_mov_b32_e32 v125, v145
	v_mov_b32_e32 v124, v145
	v_mov_b32_e32 v123, v145
	v_mov_b32_e32 v122, v145
	v_mov_b32_e32 v113, v145
	v_mov_b32_e32 v112, v145
	v_mov_b32_e32 v111, v145
	v_mov_b32_e32 v110, v145
	v_mov_b32_e32 v109, v145
	v_mov_b32_e32 v108, v145
	v_mov_b32_e32 v107, v145
	v_mov_b32_e32 v106, v145
	v_mov_b32_e32 v81, v145
	v_mov_b32_e32 v80, v145
	v_mov_b32_e32 v79, v145
	v_mov_b32_e32 v78, v145
	v_mov_b32_e32 v77, v145
	v_mov_b32_e32 v76, v145
	v_mov_b32_e32 v75, v145
	v_mov_b32_e32 v74, v145
	v_mov_b32_e32 v137, v145
	v_mov_b32_e32 v136, v145
	v_mov_b32_e32 v135, v145
	v_mov_b32_e32 v134, v145
	v_mov_b32_e32 v133, v145
	v_mov_b32_e32 v132, v145
	v_mov_b32_e32 v131, v145
	v_mov_b32_e32 v130, v145
	v_mov_b32_e32 v121, v145
	v_mov_b32_e32 v120, v145
	v_mov_b32_e32 v119, v145
	v_mov_b32_e32 v118, v145
	v_mov_b32_e32 v117, v145
	v_mov_b32_e32 v116, v145
	v_mov_b32_e32 v115, v145
	v_mov_b32_e32 v114, v145
	v_mov_b32_e32 v105, v145
	v_mov_b32_e32 v104, v145
	v_mov_b32_e32 v103, v145
	v_mov_b32_e32 v102, v145
	v_mov_b32_e32 v101, v145
	v_mov_b32_e32 v100, v145
	v_mov_b32_e32 v99, v145
	v_mov_b32_e32 v98, v145
	v_mov_b32_e32 v73, v145
	v_mov_b32_e32 v72, v145
	v_mov_b32_e32 v71, v145
	v_mov_b32_e32 v70, v145
	v_mov_b32_e32 v69, v145
	v_mov_b32_e32 v68, v145
	v_mov_b32_e32 v67, v145
	v_mov_b32_e32 v66, v145
	v_mov_b32_e32 v65, v145
	v_mov_b32_e32 v64, v145
	v_mov_b32_e32 v63, v145
	v_mov_b32_e32 v62, v145
	v_mov_b32_e32 v61, v145
	v_mov_b32_e32 v60, v145
	v_mov_b32_e32 v59, v145
	v_mov_b32_e32 v58, v145
	v_mov_b32_e32 v49, v145
	v_mov_b32_e32 v48, v145
	v_mov_b32_e32 v47, v145
	v_mov_b32_e32 v46, v145
	v_mov_b32_e32 v45, v145
	v_mov_b32_e32 v44, v145
	v_mov_b32_e32 v43, v145
	v_mov_b32_e32 v42, v145
	v_mov_b32_e32 v33, v145
	v_mov_b32_e32 v32, v145
	v_mov_b32_e32 v31, v145
	v_mov_b32_e32 v30, v145
	v_mov_b32_e32 v29, v145
	v_mov_b32_e32 v28, v145
	v_mov_b32_e32 v27, v145
	v_mov_b32_e32 v26, v145
	v_mov_b32_e32 v17, v145
	v_mov_b32_e32 v16, v145
	v_mov_b32_e32 v15, v145
	v_mov_b32_e32 v14, v145
	v_mov_b32_e32 v13, v145
	v_mov_b32_e32 v12, v145
	v_mov_b32_e32 v11, v145
	v_mov_b32_e32 v10, v145
	v_mov_b32_e32 v57, v145
	v_mov_b32_e32 v56, v145
	v_mov_b32_e32 v55, v145
	v_mov_b32_e32 v54, v145
	v_mov_b32_e32 v53, v145
	v_mov_b32_e32 v52, v145
	v_mov_b32_e32 v51, v145
	v_mov_b32_e32 v50, v145
	v_mov_b32_e32 v41, v145
	v_mov_b32_e32 v40, v145
	v_mov_b32_e32 v39, v145
	v_mov_b32_e32 v38, v145
	v_mov_b32_e32 v37, v145
	v_mov_b32_e32 v36, v145
	v_mov_b32_e32 v35, v145
	v_mov_b32_e32 v34, v145
	v_mov_b32_e32 v25, v145
	v_mov_b32_e32 v24, v145
	v_mov_b32_e32 v23, v145
	v_mov_b32_e32 v22, v145
	v_mov_b32_e32 v21, v145
	v_mov_b32_e32 v20, v145
	v_mov_b32_e32 v19, v145
	v_mov_b32_e32 v18, v145
	v_mov_b32_e32 v9, v145
	v_mov_b32_e32 v8, v145
	v_mov_b32_e32 v7, v145
	v_mov_b32_e32 v6, v145
	v_mov_b32_e32 v5, v145
	v_mov_b32_e32 v4, v145
	v_mov_b32_e32 v3, v145
	v_mov_b32_e32 v2, v145
	s_barrier
; template <class Epi, class Sched>
; DI void gemm_phase(LAS unsigned char* lds, const Gemm g, const Sched& S, const Epi& E) {
;     ...
;   const int nt = K / BK;
;   unsigned voffA[2], voffB[2];
; #pragma unroll
;   for (int i = 0; i < 2; ++i) {
;     int R, C; stage_rc(tid * 16 + i * 8192, R, C);
;     int Rb = R;
;     if (Epi::BMAP == 1) Rb = (R & ~31) + perm32(R & 31);
;     if (Epi::BMAP == 2) Rb = 64 * (R >> 5) + perm32(R & 31);
;     voffA[i] = (unsigned)(R * K + C) * 2u; voffB[i] = (unsigned)(Rb * K + C) * 2u;
;   }
;   const size_t kstep = (size_t)(BK * 2);
;   const size_t hstep = (size_t)HALF * K * 2;
;   const size_t hstepB = (Epi::BMAP == 2) ? (size_t)32 * K * 2 : hstep;
;   const size_t tstep = 2 * hstep;
;   const unsigned ldsw = (unsigned)wid * 1024u;
;   const int aoff = lds_byte(wr * 64 + fr, fq * 8), boff = lds_byte(wc * 32 + fr, fq * 8);
;     ...
; #pragma unroll
;   for (int a = 0; a < 2; ++a)
; #pragma unroll
;     for (int b = 0; b < 2; ++b)
; #pragma unroll
;       for (int m = 0; m < 4; ++m)
; #pragma unroll
;         for (int n = 0; n < 2; ++n) acc[a][b][m][n] = (f32x4){0.f, 0.f, 0.f, 0.f};
	s_cbranch_scc1 .LBB0_832
	s_lshr_b32 s9, s9, 26
	s_add_i32 s9, s8, s9
	v_or_b32_e32 v2, s15, v150
	s_ashr_i32 s24, s9, 6
	v_lshlrev_b32_e32 v3, 6, v2
	v_lshlrev_b32_e32 v4, 4, v148
	s_movk_i32 s9, 0x3c0
	v_lshlrev_b32_e32 v2, 2, v2
	v_and_or_b32 v3, v3, s9, v4
	s_lshl_b32 s9, s12, 13
	v_and_b32_e32 v2, 32, v2
	v_bitop3_b32 v5, v3, s9, v2 bitop3:0xde
	v_lshlrev_b32_e32 v3, 2, v150
	v_lshl_or_b32 v2, v150, 6, v4
	s_lshl_b32 s9, s16, 12
	v_and_b32_e32 v3, 32, v3
	v_readlane_b32 s10, v253, 35
	s_add_i32 s25, s24, -2
	v_bitop3_b32 v92, v2, s9, v3 bitop3:0xde
	s_mul_hi_i32 s9, s10, s8
	s_mul_i32 s8, s10, s8
	v_add_u32_e32 v2, v94, v88
	s_add_u32 s8, s86, s8
	v_add_lshl_u32 v2, v2, v89, 1
	v_mov_b32_e32 v3, v1
	s_addc_u32 s9, s87, s9
	v_lshl_add_u64 v[88:89], s[8:9], 0, v[2:3]
	v_add_u32_e32 v2, v93, v90
	v_add_lshl_u32 v2, v2, v91, 1
	v_lshl_add_u64 v[90:91], s[8:9], 0, v[2:3]
	v_mov_b32_e32 v2, 0
	s_mov_b32 s10, 0
	s_mov_b64 s[8:9], 0x2000080
	v_add_u32_e32 v93, 16, v5
	v_mov_b32_e32 v3, v2
	v_mov_b32_e32 v4, v2
	v_mov_b32_e32 v5, v2
	v_mov_b32_e32 v6, v2
	v_mov_b32_e32 v7, v2
	v_mov_b32_e32 v8, v2
	v_mov_b32_e32 v9, v2
	v_mov_b32_e32 v18, v2
	v_mov_b32_e32 v19, v2
	v_mov_b32_e32 v20, v2
	v_mov_b32_e32 v21, v2
	v_mov_b32_e32 v22, v2
	v_mov_b32_e32 v23, v2
	v_mov_b32_e32 v24, v2
	v_mov_b32_e32 v25, v2
	v_mov_b32_e32 v34, v2
	v_mov_b32_e32 v35, v2
	v_mov_b32_e32 v36, v2
	v_mov_b32_e32 v37, v2
	v_mov_b32_e32 v38, v2
	v_mov_b32_e32 v39, v2
	v_mov_b32_e32 v40, v2
	v_mov_b32_e32 v41, v2
	v_mov_b32_e32 v50, v2
	v_mov_b32_e32 v51, v2
	v_mov_b32_e32 v52, v2
	v_mov_b32_e32 v53, v2
	v_mov_b32_e32 v54, v2
	v_mov_b32_e32 v55, v2
	v_mov_b32_e32 v56, v2
	v_mov_b32_e32 v57, v2
	v_mov_b32_e32 v10, v2
	v_mov_b32_e32 v11, v2
	v_mov_b32_e32 v12, v2
	v_mov_b32_e32 v13, v2
	v_mov_b32_e32 v14, v2
	v_mov_b32_e32 v15, v2
	v_mov_b32_e32 v16, v2
	v_mov_b32_e32 v17, v2
	v_mov_b32_e32 v26, v2
	v_mov_b32_e32 v27, v2
	v_mov_b32_e32 v28, v2
	v_mov_b32_e32 v29, v2
	v_mov_b32_e32 v30, v2
	v_mov_b32_e32 v31, v2
	v_mov_b32_e32 v32, v2
	v_mov_b32_e32 v33, v2
	v_mov_b32_e32 v42, v2
	v_mov_b32_e32 v43, v2
	v_mov_b32_e32 v44, v2
	v_mov_b32_e32 v45, v2
	v_mov_b32_e32 v46, v2
	v_mov_b32_e32 v47, v2
	v_mov_b32_e32 v48, v2
	v_mov_b32_e32 v49, v2
	v_mov_b32_e32 v58, v2
	v_mov_b32_e32 v59, v2
	v_mov_b32_e32 v60, v2
	v_mov_b32_e32 v61, v2
	v_mov_b32_e32 v62, v2
	v_mov_b32_e32 v63, v2
	v_mov_b32_e32 v64, v2
	v_mov_b32_e32 v65, v2
	v_mov_b32_e32 v66, v2
	v_mov_b32_e32 v67, v2
	v_mov_b32_e32 v68, v2
	v_mov_b32_e32 v69, v2
	v_mov_b32_e32 v70, v2
	v_mov_b32_e32 v71, v2
	v_mov_b32_e32 v72, v2
	v_mov_b32_e32 v73, v2
	v_mov_b32_e32 v98, v2
	v_mov_b32_e32 v99, v2
	v_mov_b32_e32 v100, v2
	v_mov_b32_e32 v101, v2
	v_mov_b32_e32 v102, v2
	v_mov_b32_e32 v103, v2
	v_mov_b32_e32 v104, v2
	v_mov_b32_e32 v105, v2
	v_mov_b32_e32 v114, v2
	v_mov_b32_e32 v115, v2
	v_mov_b32_e32 v116, v2
	v_mov_b32_e32 v117, v2
	v_mov_b32_e32 v118, v2
	v_mov_b32_e32 v119, v2
	v_mov_b32_e32 v120, v2
	v_mov_b32_e32 v121, v2
	v_mov_b32_e32 v130, v2
	v_mov_b32_e32 v131, v2
	v_mov_b32_e32 v132, v2
	v_mov_b32_e32 v133, v2
	v_mov_b32_e32 v134, v2
	v_mov_b32_e32 v135, v2
	v_mov_b32_e32 v136, v2
	v_mov_b32_e32 v137, v2
	v_mov_b32_e32 v74, v2
	v_mov_b32_e32 v75, v2
	v_mov_b32_e32 v76, v2
	v_mov_b32_e32 v77, v2
	v_mov_b32_e32 v78, v2
	v_mov_b32_e32 v79, v2
	v_mov_b32_e32 v80, v2
	v_mov_b32_e32 v81, v2
	v_mov_b32_e32 v106, v2
	v_mov_b32_e32 v107, v2
	v_mov_b32_e32 v108, v2
	v_mov_b32_e32 v109, v2
	v_mov_b32_e32 v110, v2
	v_mov_b32_e32 v111, v2
	v_mov_b32_e32 v112, v2
	v_mov_b32_e32 v113, v2
	v_mov_b32_e32 v122, v2
	v_mov_b32_e32 v123, v2
	v_mov_b32_e32 v124, v2
	v_mov_b32_e32 v125, v2
	v_mov_b32_e32 v126, v2
	v_mov_b32_e32 v127, v2
	v_mov_b32_e32 v128, v2
	v_mov_b32_e32 v129, v2
	v_mov_b32_e32 v138, v2
	v_mov_b32_e32 v139, v2
	v_mov_b32_e32 v140, v2
	v_mov_b32_e32 v141, v2
	v_mov_b32_e32 v142, v2
	v_mov_b32_e32 v143, v2
	v_mov_b32_e32 v144, v2
	v_mov_b32_e32 v145, v2
	.p2align	8

; __global__ void __launch_bounds__(512, 2) fwd_megakernel(Params p) {
;   extern __shared__ __attribute__((aligned(16))) unsigned char dsm[];
	.section	.rodata,"a",@progbits
	.p2align	8, 0x0
